# conv LayerNorm tail batched over 8 tokens with DPP sums + GEMM1/GEMM3 epilogues store from registers via lane-pair exchange (no LDS staging)
# speedup vs baseline: 1.0102x; 1.0102x over previous
; #define LAS __attribute__((address_space(3)))
; __device__ __forceinline__ unsigned cvt_pk_bf16(float lo, float hi) { unsigned r; asm volatile("v_cvt_pk_bf16_f32 %0, %1, %2" : "=v"(r) : "v"(lo), "v"(hi)); return r; }
; __device__ __forceinline__ float rinv_from(u64 v) { return rsqrtf((float)v * (1.0f / 16777216.0f) * (1.0f / 1024.0f) + RMS_EPS); }
;     __device__ __forceinline__ void operator()(const f32x4 (&acc)[2][2][4][2], const Unit& u, int wr, int wc, int fr, int fq) const {
;         const int ln = fr + 16 * fq; const int colw = u.pn * BM + 64 * wc;
;         if (colw >= nvalid) return;
;         float rl[2];
; #pragma unroll
;         for (int ai = 0; ai < 2; ++ai) rl[ai] = rinv_from(ssq[u.pm * BM + ai * HALF + wr * 64 + ln]);
;         LAS unsigned char* sl = stg + (wr * 4 + wc) * EPI_STG_SLICE;
;         const int rr = ln >> 3, cc = ln & 7;
; #pragma unroll
;         for (int ai = 0; ai < 2; ++ai)
; #pragma unroll
;             for (int m = 0; m < 4; ++m) {
;                 const float sc = __shfl(rl[ai], 16 * m + fr);
; #pragma unroll
;                 for (int bj = 0; bj < 2; ++bj) {
;                     f32x4 v0 = acc[ai][bj][m][0] * sc, v1 = acc[ai][bj][m][1] * sc;
;                     if (ACT == 1) {
; #pragma unroll
;                         for (int e = 0; e < 4; ++e) { float a = fmaxf(v0[e], 0.f), b = fmaxf(v1[e], 0.f); v0[e] = a * a; v1[e] = b * b; }
;                     }
;                     u32x4 w; w.x = cvt_pk_bf16(v0[0], v0[1]); w.y = cvt_pk_bf16(v0[2], v0[3]); w.z = cvt_pk_bf16(v1[0], v1[1]); w.w = cvt_pk_bf16(v1[2], v1[3]);
;                     *(LAS u32x4*)(sl + fr * 144 + bj * 64 + fq * 16) = w;
;                 }
;                 const int rowb = u.pm * BM + ai * HALF + wr * 64 + m * 16;
; #pragma unroll
;                 for (int i = 0; i < 2; ++i) { const int r = rr + 8 * i; const u32x4 q = *(const LAS u32x4*)(sl + r * 144 + cc * 16);
;                     __builtin_nontemporal_store(q, (u32x4*)(O + (size_t)(rowb + r) * ldc + colw + cc * 8)); }
.LBB0_114:
	s_lshl_b32 s3, s2, 8
	v_add_u32_e32 v162, s3, v155
	v_ashrrev_i32_e32 v163, 31, v162
	v_lshl_add_u64 v[162:163], v[162:163], 3, s[42:43]
	global_load_dwordx2 v[164:165], v[162:163], off
	s_nop 0
	global_load_dwordx2 v[162:163], v[162:163], off offset:1024
	s_mov_b32 s2, 0x33800000
	s_ashr_i32 s27, s26, 31
	s_add_i32 s6, s3, s81
	s_waitcnt vmcnt(0)
	v_ffbh_u32_e32 v153, v165
	v_min_u32_e32 v153, 32, v153
	v_lshlrev_b64 v[164:165], v153, v[164:165]
	v_min_u32_e32 v161, 1, v164
	v_or_b32_e32 v161, v165, v161
	v_cvt_f32_u32_e32 v161, v161
	v_sub_u32_e32 v153, 32, v153
	v_ldexp_f32 v165, v161, v153
	v_ffbh_u32_e32 v153, v163
	v_min_u32_e32 v153, 32, v153
	v_lshlrev_b64 v[162:163], v153, v[162:163]
	v_min_u32_e32 v161, 1, v162
	v_or_b32_e32 v161, v163, v161
	v_cvt_f32_u32_e32 v161, v161
	v_sub_u32_e32 v153, 32, v153
	v_ldexp_f32 v164, v161, v153
	v_pk_mul_f32 v[162:163], v[164:165], s[2:3] op_sel_hi:[1,0]
	s_mov_b32 s2, 0x3a800000
	v_pk_fma_f32 v[162:163], v[162:163], s[2:3], v[138:139] op_sel_hi:[1,0,0]
	s_add_i32 s2, s3, s77
	v_mul_f32_e32 v153, 0x4b800000, v163
	v_cmp_gt_f32_e64 s[38:39], s70, v163
	v_cmp_gt_f32_e32 vcc, s70, v162
	s_nop 0
	v_cndmask_b32_e64 v153, v163, v153, s[38:39]
	v_rsq_f32_e32 v153, v153
	s_nop 0
	v_mul_f32_e32 v161, 0x45800000, v153
	v_cndmask_b32_e64 v163, v153, v161, s[38:39]
	v_mul_f32_e32 v153, 0x4b800000, v162
	v_cndmask_b32_e32 v153, v162, v153, vcc
	v_rsq_f32_e32 v153, v153
	s_lshl_b64 s[38:39], s[26:27], 1
	v_mul_f32_e32 v161, 0x45800000, v153
	v_cndmask_b32_e32 v161, v153, v161, vcc
	v_and_or_b32 v153, v177, 64, v1
	v_lshlrev_b32_e32 v162, 2, v153
	ds_bpermute_b32 v192, v162, v163
	ds_bpermute_b32 v194, v162, v163 offset:64
	ds_bpermute_b32 v196, v162, v163 offset:128
	ds_bpermute_b32 v198, v162, v163 offset:192
	ds_bpermute_b32 v200, v162, v161
	ds_bpermute_b32 v202, v162, v161 offset:64
	ds_bpermute_b32 v204, v162, v161 offset:128
	ds_bpermute_b32 v206, v162, v161 offset:192
	v_and_b32_e32 v210, 1, v177
	v_and_b32_e32 v211, 14, v177
	v_cmp_eq_u32_e64 s[92:93], 0, v210
	v_mul_u32_u24_e32 v208, 0x1300, v211
	s_mul_i32 s7, s2, 0x1300
	v_lshl_add_u32 v208, v210, 6, v208
	v_bfe_u32 v211, v177, 4, 2
	v_lshl_add_u32 v208, v211, 4, v208
	v_add_u32_e32 v209, 0x1300, v208
	s_add_u32 s62, s40, s7
	s_addc_u32 s63, s41, 0
	s_lshl_b32 s7, s26, 1
	s_add_u32 s62, s62, s7
	s_addc_u32 s63, s63, 0
	s_waitcnt lgkmcnt(7)
	s_mov_b32 s64, s62
	s_mov_b32 s65, s63
	v_pk_mul_f32 v[126:127], v[126:127], v[192:193] op_sel_hi:[1,0]
	v_pk_mul_f32 v[128:129], v[128:129], v[192:193] op_sel_hi:[1,0]
	v_pk_mul_f32 v[122:123], v[122:123], v[192:193] op_sel_hi:[1,0]
	v_pk_mul_f32 v[124:125], v[124:125], v[192:193] op_sel_hi:[1,0]
	v_cvt_pk_bf16_f32 v126, v126, v127
	v_cvt_pk_bf16_f32 v127, v128, v129
	v_cvt_pk_bf16_f32 v128, v122, v123
	v_cvt_pk_bf16_f32 v129, v124, v125
	v_pk_mul_f32 v[118:119], v[118:119], v[192:193] op_sel_hi:[1,0]
	v_pk_mul_f32 v[120:121], v[120:121], v[192:193] op_sel_hi:[1,0]
	v_pk_mul_f32 v[114:115], v[114:115], v[192:193] op_sel_hi:[1,0]
	v_pk_mul_f32 v[116:117], v[116:117], v[192:193] op_sel_hi:[1,0]
	v_cvt_pk_bf16_f32 v118, v118, v119
	v_cvt_pk_bf16_f32 v119, v120, v121
	v_cvt_pk_bf16_f32 v120, v114, v115
	v_cvt_pk_bf16_f32 v121, v116, v117
	v_cndmask_b32_e64 v122, v126, v118, s[92:93]
	v_cndmask_b32_e64 v123, v127, v119, s[92:93]
	v_cndmask_b32_e64 v124, v128, v120, s[92:93]
	v_cndmask_b32_e64 v125, v129, v121, s[92:93]
	v_mov_b32_dpp v114, v122 quad_perm:[1,0,3,2] row_mask:0xf bank_mask:0xf
	v_mov_b32_dpp v115, v123 quad_perm:[1,0,3,2] row_mask:0xf bank_mask:0xf
	v_mov_b32_dpp v116, v124 quad_perm:[1,0,3,2] row_mask:0xf bank_mask:0xf
	v_mov_b32_dpp v117, v125 quad_perm:[1,0,3,2] row_mask:0xf bank_mask:0xf
	v_cndmask_b32_e64 v126, v114, v126, s[92:93]
	v_cndmask_b32_e64 v127, v115, v127, s[92:93]
	v_cndmask_b32_e64 v128, v116, v128, s[92:93]
	v_cndmask_b32_e64 v129, v117, v129, s[92:93]
	v_cndmask_b32_e64 v118, v118, v114, s[92:93]
	v_cndmask_b32_e64 v119, v119, v115, s[92:93]
	v_cndmask_b32_e64 v120, v120, v116, s[92:93]
	v_cndmask_b32_e64 v121, v121, v117, s[92:93]
	global_store_dwordx4 v208, v[126:129], s[64:65] nt
	global_store_dwordx4 v209, v[118:121], s[64:65] nt
	s_waitcnt lgkmcnt(6)
	s_add_u32 s64, s62, 0x13000
	s_addc_u32 s65, s63, 0
	v_pk_mul_f32 v[110:111], v[110:111], v[194:195] op_sel_hi:[1,0]
	v_pk_mul_f32 v[112:113], v[112:113], v[194:195] op_sel_hi:[1,0]
	v_pk_mul_f32 v[106:107], v[106:107], v[194:195] op_sel_hi:[1,0]
	v_pk_mul_f32 v[108:109], v[108:109], v[194:195] op_sel_hi:[1,0]
	v_cvt_pk_bf16_f32 v110, v110, v111
	v_cvt_pk_bf16_f32 v111, v112, v113
	v_cvt_pk_bf16_f32 v112, v106, v107
	v_cvt_pk_bf16_f32 v113, v108, v109
	v_pk_mul_f32 v[102:103], v[102:103], v[194:195] op_sel_hi:[1,0]
	v_pk_mul_f32 v[104:105], v[104:105], v[194:195] op_sel_hi:[1,0]
	v_pk_mul_f32 v[98:99], v[98:99], v[194:195] op_sel_hi:[1,0]
	v_pk_mul_f32 v[100:101], v[100:101], v[194:195] op_sel_hi:[1,0]
	v_cvt_pk_bf16_f32 v102, v102, v103
	v_cvt_pk_bf16_f32 v103, v104, v105
	v_cvt_pk_bf16_f32 v104, v98, v99
	v_cvt_pk_bf16_f32 v105, v100, v101
	v_cndmask_b32_e64 v106, v110, v102, s[92:93]
	v_cndmask_b32_e64 v107, v111, v103, s[92:93]
	v_cndmask_b32_e64 v108, v112, v104, s[92:93]
	v_cndmask_b32_e64 v109, v113, v105, s[92:93]
	v_mov_b32_dpp v98, v106 quad_perm:[1,0,3,2] row_mask:0xf bank_mask:0xf
	v_mov_b32_dpp v99, v107 quad_perm:[1,0,3,2] row_mask:0xf bank_mask:0xf
	v_mov_b32_dpp v100, v108 quad_perm:[1,0,3,2] row_mask:0xf bank_mask:0xf
	v_mov_b32_dpp v101, v109 quad_perm:[1,0,3,2] row_mask:0xf bank_mask:0xf
	v_cndmask_b32_e64 v110, v98, v110, s[92:93]
	v_cndmask_b32_e64 v111, v99, v111, s[92:93]
	v_cndmask_b32_e64 v112, v100, v112, s[92:93]
	v_cndmask_b32_e64 v113, v101, v113, s[92:93]
	v_cndmask_b32_e64 v102, v102, v98, s[92:93]
	v_cndmask_b32_e64 v103, v103, v99, s[92:93]
	v_cndmask_b32_e64 v104, v104, v100, s[92:93]
	v_cndmask_b32_e64 v105, v105, v101, s[92:93]
	global_store_dwordx4 v208, v[110:113], s[64:65] nt
	global_store_dwordx4 v209, v[102:105], s[64:65] nt
	s_waitcnt lgkmcnt(5)
; #define LAS __attribute__((address_space(3)))
; __device__ __forceinline__ unsigned cvt_pk_bf16(float lo, float hi) { unsigned r; asm volatile("v_cvt_pk_bf16_f32 %0, %1, %2" : "=v"(r) : "v"(lo), "v"(hi)); return r; }
;     __device__ __forceinline__ void operator()(const f32x4 (&acc)[2][2][4][2], const Unit& u, int wr, int wc, int fr, int fq) const {
;     ...
;         for (int ai = 0; ai < 2; ++ai)
; #pragma unroll
;             for (int m = 0; m < 4; ++m) {
;                 const float sc = __shfl(rl[ai], 16 * m + fr);
; #pragma unroll
;                 for (int bj = 0; bj < 2; ++bj) {
;                     f32x4 v0 = acc[ai][bj][m][0] * sc, v1 = acc[ai][bj][m][1] * sc;
;                     if (ACT == 1) {
; #pragma unroll
;                         for (int e = 0; e < 4; ++e) { float a = fmaxf(v0[e], 0.f), b = fmaxf(v1[e], 0.f); v0[e] = a * a; v1[e] = b * b; }
;                     }
;                     u32x4 w; w.x = cvt_pk_bf16(v0[0], v0[1]); w.y = cvt_pk_bf16(v0[2], v0[3]); w.z = cvt_pk_bf16(v1[0], v1[1]); w.w = cvt_pk_bf16(v1[2], v1[3]);
;                     *(LAS u32x4*)(sl + fr * 144 + bj * 64 + fq * 16) = w;
;                 }
;                 const int rowb = u.pm * BM + ai * HALF + wr * 64 + m * 16;
; #pragma unroll
;                 for (int i = 0; i < 2; ++i) { const int r = rr + 8 * i; const u32x4 q = *(const LAS u32x4*)(sl + r * 144 + cc * 16);
;                     __builtin_nontemporal_store(q, (u32x4*)(O + (size_t)(rowb + r) * ldc + colw + cc * 8)); }
	s_add_u32 s64, s62, 0x26000
	s_addc_u32 s65, s63, 0
	v_pk_mul_f32 v[94:95], v[94:95], v[196:197] op_sel_hi:[1,0]
	v_pk_mul_f32 v[96:97], v[96:97], v[196:197] op_sel_hi:[1,0]
	v_pk_mul_f32 v[90:91], v[90:91], v[196:197] op_sel_hi:[1,0]
	v_pk_mul_f32 v[92:93], v[92:93], v[196:197] op_sel_hi:[1,0]
	v_cvt_pk_bf16_f32 v94, v94, v95
	v_cvt_pk_bf16_f32 v95, v96, v97
	v_cvt_pk_bf16_f32 v96, v90, v91
	v_cvt_pk_bf16_f32 v97, v92, v93
	v_pk_mul_f32 v[86:87], v[86:87], v[196:197] op_sel_hi:[1,0]
	v_pk_mul_f32 v[88:89], v[88:89], v[196:197] op_sel_hi:[1,0]
	v_pk_mul_f32 v[82:83], v[82:83], v[196:197] op_sel_hi:[1,0]
	v_pk_mul_f32 v[84:85], v[84:85], v[196:197] op_sel_hi:[1,0]
	v_cvt_pk_bf16_f32 v86, v86, v87
	v_cvt_pk_bf16_f32 v87, v88, v89
	v_cvt_pk_bf16_f32 v88, v82, v83
	v_cvt_pk_bf16_f32 v89, v84, v85
	v_cndmask_b32_e64 v90, v94, v86, s[92:93]
	v_cndmask_b32_e64 v91, v95, v87, s[92:93]
	v_cndmask_b32_e64 v92, v96, v88, s[92:93]
	v_cndmask_b32_e64 v93, v97, v89, s[92:93]
	v_mov_b32_dpp v82, v90 quad_perm:[1,0,3,2] row_mask:0xf bank_mask:0xf
	v_mov_b32_dpp v83, v91 quad_perm:[1,0,3,2] row_mask:0xf bank_mask:0xf
	v_mov_b32_dpp v84, v92 quad_perm:[1,0,3,2] row_mask:0xf bank_mask:0xf
	v_mov_b32_dpp v85, v93 quad_perm:[1,0,3,2] row_mask:0xf bank_mask:0xf
	v_cndmask_b32_e64 v94, v82, v94, s[92:93]
	v_cndmask_b32_e64 v95, v83, v95, s[92:93]
	v_cndmask_b32_e64 v96, v84, v96, s[92:93]
	v_cndmask_b32_e64 v97, v85, v97, s[92:93]
	v_cndmask_b32_e64 v86, v86, v82, s[92:93]
	v_cndmask_b32_e64 v87, v87, v83, s[92:93]
	v_cndmask_b32_e64 v88, v88, v84, s[92:93]
	v_cndmask_b32_e64 v89, v89, v85, s[92:93]
	global_store_dwordx4 v208, v[94:97], s[64:65] nt
	global_store_dwordx4 v209, v[86:89], s[64:65] nt
	s_waitcnt lgkmcnt(4)
	s_add_u32 s64, s62, 0x39000
	s_addc_u32 s65, s63, 0
	v_pk_mul_f32 v[78:79], v[78:79], v[198:199] op_sel_hi:[1,0]
	v_pk_mul_f32 v[80:81], v[80:81], v[198:199] op_sel_hi:[1,0]
	v_pk_mul_f32 v[74:75], v[74:75], v[198:199] op_sel_hi:[1,0]
	v_pk_mul_f32 v[76:77], v[76:77], v[198:199] op_sel_hi:[1,0]
	v_cvt_pk_bf16_f32 v78, v78, v79
	v_cvt_pk_bf16_f32 v79, v80, v81
	v_cvt_pk_bf16_f32 v80, v74, v75
	v_cvt_pk_bf16_f32 v81, v76, v77
	v_pk_mul_f32 v[70:71], v[70:71], v[198:199] op_sel_hi:[1,0]
	v_pk_mul_f32 v[72:73], v[72:73], v[198:199] op_sel_hi:[1,0]
	v_pk_mul_f32 v[66:67], v[66:67], v[198:199] op_sel_hi:[1,0]
	v_pk_mul_f32 v[68:69], v[68:69], v[198:199] op_sel_hi:[1,0]
	v_cvt_pk_bf16_f32 v70, v70, v71
	v_cvt_pk_bf16_f32 v71, v72, v73
	v_cvt_pk_bf16_f32 v72, v66, v67
	v_cvt_pk_bf16_f32 v73, v68, v69
	v_cndmask_b32_e64 v74, v78, v70, s[92:93]
	v_cndmask_b32_e64 v75, v79, v71, s[92:93]
	v_cndmask_b32_e64 v76, v80, v72, s[92:93]
	v_cndmask_b32_e64 v77, v81, v73, s[92:93]
	v_mov_b32_dpp v66, v74 quad_perm:[1,0,3,2] row_mask:0xf bank_mask:0xf
	v_mov_b32_dpp v67, v75 quad_perm:[1,0,3,2] row_mask:0xf bank_mask:0xf
	v_mov_b32_dpp v68, v76 quad_perm:[1,0,3,2] row_mask:0xf bank_mask:0xf
	v_mov_b32_dpp v69, v77 quad_perm:[1,0,3,2] row_mask:0xf bank_mask:0xf
	v_cndmask_b32_e64 v78, v66, v78, s[92:93]
	v_cndmask_b32_e64 v79, v67, v79, s[92:93]
	v_cndmask_b32_e64 v80, v68, v80, s[92:93]
	v_cndmask_b32_e64 v81, v69, v81, s[92:93]
	v_cndmask_b32_e64 v70, v70, v66, s[92:93]
	v_cndmask_b32_e64 v71, v71, v67, s[92:93]
	v_cndmask_b32_e64 v72, v72, v68, s[92:93]
	v_cndmask_b32_e64 v73, v73, v69, s[92:93]
	global_store_dwordx4 v208, v[78:81], s[64:65] nt
	global_store_dwordx4 v209, v[70:73], s[64:65] nt
	s_waitcnt lgkmcnt(3)
	s_add_u32 s64, s62, 0x98000
	s_addc_u32 s65, s63, 0
	v_pk_mul_f32 v[62:63], v[62:63], v[200:201] op_sel_hi:[1,0]
	v_pk_mul_f32 v[64:65], v[64:65], v[200:201] op_sel_hi:[1,0]
	v_pk_mul_f32 v[58:59], v[58:59], v[200:201] op_sel_hi:[1,0]
	v_pk_mul_f32 v[60:61], v[60:61], v[200:201] op_sel_hi:[1,0]
	v_cvt_pk_bf16_f32 v62, v62, v63
	v_cvt_pk_bf16_f32 v63, v64, v65
	v_cvt_pk_bf16_f32 v64, v58, v59
	v_cvt_pk_bf16_f32 v65, v60, v61
	v_pk_mul_f32 v[54:55], v[54:55], v[200:201] op_sel_hi:[1,0]
	v_pk_mul_f32 v[56:57], v[56:57], v[200:201] op_sel_hi:[1,0]
	v_pk_mul_f32 v[50:51], v[50:51], v[200:201] op_sel_hi:[1,0]
	v_pk_mul_f32 v[52:53], v[52:53], v[200:201] op_sel_hi:[1,0]
	v_cvt_pk_bf16_f32 v54, v54, v55
	v_cvt_pk_bf16_f32 v55, v56, v57
	v_cvt_pk_bf16_f32 v56, v50, v51
	v_cvt_pk_bf16_f32 v57, v52, v53
	v_cndmask_b32_e64 v58, v62, v54, s[92:93]
	v_cndmask_b32_e64 v59, v63, v55, s[92:93]
	v_cndmask_b32_e64 v60, v64, v56, s[92:93]
	v_cndmask_b32_e64 v61, v65, v57, s[92:93]
	v_mov_b32_dpp v50, v58 quad_perm:[1,0,3,2] row_mask:0xf bank_mask:0xf
	v_mov_b32_dpp v51, v59 quad_perm:[1,0,3,2] row_mask:0xf bank_mask:0xf
	v_mov_b32_dpp v52, v60 quad_perm:[1,0,3,2] row_mask:0xf bank_mask:0xf
	v_mov_b32_dpp v53, v61 quad_perm:[1,0,3,2] row_mask:0xf bank_mask:0xf
	v_cndmask_b32_e64 v62, v50, v62, s[92:93]
	v_cndmask_b32_e64 v63, v51, v63, s[92:93]
	v_cndmask_b32_e64 v64, v52, v64, s[92:93]
	v_cndmask_b32_e64 v65, v53, v65, s[92:93]
	v_cndmask_b32_e64 v54, v54, v50, s[92:93]
	v_cndmask_b32_e64 v55, v55, v51, s[92:93]
	v_cndmask_b32_e64 v56, v56, v52, s[92:93]
	v_cndmask_b32_e64 v57, v57, v53, s[92:93]
	global_store_dwordx4 v208, v[62:65], s[64:65] nt
	global_store_dwordx4 v209, v[54:57], s[64:65] nt
	s_waitcnt lgkmcnt(2)
; #define LAS __attribute__((address_space(3)))
; __device__ __forceinline__ unsigned cvt_pk_bf16(float lo, float hi) { unsigned r; asm volatile("v_cvt_pk_bf16_f32 %0, %1, %2" : "=v"(r) : "v"(lo), "v"(hi)); return r; }
;     __device__ __forceinline__ void operator()(const f32x4 (&acc)[2][2][4][2], const Unit& u, int wr, int wc, int fr, int fq) const {
;     ...
;         for (int ai = 0; ai < 2; ++ai)
; #pragma unroll
;             for (int m = 0; m < 4; ++m) {
;                 const float sc = __shfl(rl[ai], 16 * m + fr);
; #pragma unroll
;                 for (int bj = 0; bj < 2; ++bj) {
;                     f32x4 v0 = acc[ai][bj][m][0] * sc, v1 = acc[ai][bj][m][1] * sc;
;                     if (ACT == 1) {
; #pragma unroll
;                         for (int e = 0; e < 4; ++e) { float a = fmaxf(v0[e], 0.f), b = fmaxf(v1[e], 0.f); v0[e] = a * a; v1[e] = b * b; }
;                     }
;                     u32x4 w; w.x = cvt_pk_bf16(v0[0], v0[1]); w.y = cvt_pk_bf16(v0[2], v0[3]); w.z = cvt_pk_bf16(v1[0], v1[1]); w.w = cvt_pk_bf16(v1[2], v1[3]);
;                     *(LAS u32x4*)(sl + fr * 144 + bj * 64 + fq * 16) = w;
;                 }
;                 const int rowb = u.pm * BM + ai * HALF + wr * 64 + m * 16;
; #pragma unroll
;                 for (int i = 0; i < 2; ++i) { const int r = rr + 8 * i; const u32x4 q = *(const LAS u32x4*)(sl + r * 144 + cc * 16);
;                     __builtin_nontemporal_store(q, (u32x4*)(O + (size_t)(rowb + r) * ldc + colw + cc * 8)); }
	s_add_u32 s64, s62, 0xab000
	s_addc_u32 s65, s63, 0
	v_pk_mul_f32 v[46:47], v[46:47], v[202:203] op_sel_hi:[1,0]
	v_pk_mul_f32 v[48:49], v[48:49], v[202:203] op_sel_hi:[1,0]
	v_pk_mul_f32 v[42:43], v[42:43], v[202:203] op_sel_hi:[1,0]
	v_pk_mul_f32 v[44:45], v[44:45], v[202:203] op_sel_hi:[1,0]
	v_cvt_pk_bf16_f32 v46, v46, v47
	v_cvt_pk_bf16_f32 v47, v48, v49
	v_cvt_pk_bf16_f32 v48, v42, v43
	v_cvt_pk_bf16_f32 v49, v44, v45
	v_pk_mul_f32 v[38:39], v[38:39], v[202:203] op_sel_hi:[1,0]
	v_pk_mul_f32 v[40:41], v[40:41], v[202:203] op_sel_hi:[1,0]
	v_pk_mul_f32 v[34:35], v[34:35], v[202:203] op_sel_hi:[1,0]
	v_pk_mul_f32 v[36:37], v[36:37], v[202:203] op_sel_hi:[1,0]
	v_cvt_pk_bf16_f32 v38, v38, v39
	v_cvt_pk_bf16_f32 v39, v40, v41
	v_cvt_pk_bf16_f32 v40, v34, v35
	v_cvt_pk_bf16_f32 v41, v36, v37
	v_cndmask_b32_e64 v42, v46, v38, s[92:93]
	v_cndmask_b32_e64 v43, v47, v39, s[92:93]
	v_cndmask_b32_e64 v44, v48, v40, s[92:93]
	v_cndmask_b32_e64 v45, v49, v41, s[92:93]
	v_mov_b32_dpp v34, v42 quad_perm:[1,0,3,2] row_mask:0xf bank_mask:0xf
	v_mov_b32_dpp v35, v43 quad_perm:[1,0,3,2] row_mask:0xf bank_mask:0xf
	v_mov_b32_dpp v36, v44 quad_perm:[1,0,3,2] row_mask:0xf bank_mask:0xf
	v_mov_b32_dpp v37, v45 quad_perm:[1,0,3,2] row_mask:0xf bank_mask:0xf
	v_cndmask_b32_e64 v46, v34, v46, s[92:93]
	v_cndmask_b32_e64 v47, v35, v47, s[92:93]
	v_cndmask_b32_e64 v48, v36, v48, s[92:93]
	v_cndmask_b32_e64 v49, v37, v49, s[92:93]
	v_cndmask_b32_e64 v38, v38, v34, s[92:93]
	v_cndmask_b32_e64 v39, v39, v35, s[92:93]
	v_cndmask_b32_e64 v40, v40, v36, s[92:93]
	v_cndmask_b32_e64 v41, v41, v37, s[92:93]
	global_store_dwordx4 v208, v[46:49], s[64:65] nt
	global_store_dwordx4 v209, v[38:41], s[64:65] nt
	s_waitcnt lgkmcnt(1)
	s_add_u32 s64, s62, 0xbe000
	s_addc_u32 s65, s63, 0
	v_pk_mul_f32 v[30:31], v[30:31], v[204:205] op_sel_hi:[1,0]
	v_pk_mul_f32 v[32:33], v[32:33], v[204:205] op_sel_hi:[1,0]
	v_pk_mul_f32 v[26:27], v[26:27], v[204:205] op_sel_hi:[1,0]
	v_pk_mul_f32 v[28:29], v[28:29], v[204:205] op_sel_hi:[1,0]
	v_cvt_pk_bf16_f32 v30, v30, v31
	v_cvt_pk_bf16_f32 v31, v32, v33
	v_cvt_pk_bf16_f32 v32, v26, v27
	v_cvt_pk_bf16_f32 v33, v28, v29
	v_pk_mul_f32 v[22:23], v[22:23], v[204:205] op_sel_hi:[1,0]
	v_pk_mul_f32 v[24:25], v[24:25], v[204:205] op_sel_hi:[1,0]
	v_pk_mul_f32 v[18:19], v[18:19], v[204:205] op_sel_hi:[1,0]
	v_pk_mul_f32 v[20:21], v[20:21], v[204:205] op_sel_hi:[1,0]
	v_cvt_pk_bf16_f32 v22, v22, v23
	v_cvt_pk_bf16_f32 v23, v24, v25
	v_cvt_pk_bf16_f32 v24, v18, v19
	v_cvt_pk_bf16_f32 v25, v20, v21
	v_cndmask_b32_e64 v26, v30, v22, s[92:93]
	v_cndmask_b32_e64 v27, v31, v23, s[92:93]
	v_cndmask_b32_e64 v28, v32, v24, s[92:93]
	v_cndmask_b32_e64 v29, v33, v25, s[92:93]
	v_mov_b32_dpp v18, v26 quad_perm:[1,0,3,2] row_mask:0xf bank_mask:0xf
	v_mov_b32_dpp v19, v27 quad_perm:[1,0,3,2] row_mask:0xf bank_mask:0xf
	v_mov_b32_dpp v20, v28 quad_perm:[1,0,3,2] row_mask:0xf bank_mask:0xf
	v_mov_b32_dpp v21, v29 quad_perm:[1,0,3,2] row_mask:0xf bank_mask:0xf
	v_cndmask_b32_e64 v30, v18, v30, s[92:93]
	v_cndmask_b32_e64 v31, v19, v31, s[92:93]
	v_cndmask_b32_e64 v32, v20, v32, s[92:93]
	v_cndmask_b32_e64 v33, v21, v33, s[92:93]
	v_cndmask_b32_e64 v22, v22, v18, s[92:93]
	v_cndmask_b32_e64 v23, v23, v19, s[92:93]
	v_cndmask_b32_e64 v24, v24, v20, s[92:93]
	v_cndmask_b32_e64 v25, v25, v21, s[92:93]
	global_store_dwordx4 v208, v[30:33], s[64:65] nt
	global_store_dwordx4 v209, v[22:25], s[64:65] nt
	s_waitcnt lgkmcnt(0)
	s_add_u32 s64, s62, 0xd1000
	s_addc_u32 s65, s63, 0
	v_pk_mul_f32 v[14:15], v[14:15], v[206:207] op_sel_hi:[1,0]
	v_pk_mul_f32 v[16:17], v[16:17], v[206:207] op_sel_hi:[1,0]
	v_pk_mul_f32 v[10:11], v[10:11], v[206:207] op_sel_hi:[1,0]
	v_pk_mul_f32 v[12:13], v[12:13], v[206:207] op_sel_hi:[1,0]
	v_cvt_pk_bf16_f32 v14, v14, v15
	v_cvt_pk_bf16_f32 v15, v16, v17
	v_cvt_pk_bf16_f32 v16, v10, v11
	v_cvt_pk_bf16_f32 v17, v12, v13
	v_pk_mul_f32 v[6:7], v[6:7], v[206:207] op_sel_hi:[1,0]
	v_pk_mul_f32 v[8:9], v[8:9], v[206:207] op_sel_hi:[1,0]
	v_pk_mul_f32 v[2:3], v[2:3], v[206:207] op_sel_hi:[1,0]
	v_pk_mul_f32 v[4:5], v[4:5], v[206:207] op_sel_hi:[1,0]
	v_cvt_pk_bf16_f32 v6, v6, v7
	v_cvt_pk_bf16_f32 v7, v8, v9
	v_cvt_pk_bf16_f32 v8, v2, v3
	v_cvt_pk_bf16_f32 v9, v4, v5
	v_cndmask_b32_e64 v10, v14, v6, s[92:93]
	v_cndmask_b32_e64 v11, v15, v7, s[92:93]
	v_cndmask_b32_e64 v12, v16, v8, s[92:93]
	v_cndmask_b32_e64 v13, v17, v9, s[92:93]
	v_mov_b32_dpp v2, v10 quad_perm:[1,0,3,2] row_mask:0xf bank_mask:0xf
	v_mov_b32_dpp v3, v11 quad_perm:[1,0,3,2] row_mask:0xf bank_mask:0xf
	v_mov_b32_dpp v4, v12 quad_perm:[1,0,3,2] row_mask:0xf bank_mask:0xf
	v_mov_b32_dpp v5, v13 quad_perm:[1,0,3,2] row_mask:0xf bank_mask:0xf
	v_cndmask_b32_e64 v14, v2, v14, s[92:93]
	v_cndmask_b32_e64 v15, v3, v15, s[92:93]
	v_cndmask_b32_e64 v16, v4, v16, s[92:93]
	v_cndmask_b32_e64 v17, v5, v17, s[92:93]
	v_cndmask_b32_e64 v6, v6, v2, s[92:93]
	v_cndmask_b32_e64 v7, v7, v3, s[92:93]
	v_cndmask_b32_e64 v8, v8, v4, s[92:93]
	v_cndmask_b32_e64 v9, v9, v5, s[92:93]
	global_store_dwordx4 v208, v[14:17], s[64:65] nt
	global_store_dwordx4 v209, v[6:9], s[64:65] nt
	s_andn2_b64 vcc, exec, s[36:37]
	s_mov_b64 s[26:27], -1
	s_cbranch_vccnz .LBB0_105

; #define LAS __attribute__((address_space(3)))
;     static __device__ __forceinline__ void run(float (&acc)[32], const float (&wv)[31], const LAS float* U, int rb, int cch) {
;         const float uv = U[ring94(ring94(rb + S)) * 256 + cch];
; #pragma unroll
;         for (int o = 0; o < 32; ++o) { constexpr int dummy = 0; const int kk = S - o + dummy; if (kk >= 0 && kk <= 30) acc[o] += wv[kk] * uv; }
;         ConvStep<S + 1>::run(acc, wv, U, rb, cch);
; __device__ __forceinline__ void conv_loop(unsigned char* ws_, const float* const* in_, int l_, LAS unsigned char* lds, int tid, int bid, int G) {
;     ...
;             float acc[32];
; #pragma unroll
;             for (int o = 0; o < 32; ++o) acc[o] = bias;
;             const int rb = base + 32 * half;
;             ConvStep<0>::run(acc, wv, U, rb, cch);
.LBB0_302:
	v_lshl_add_u32 v188, v103, 10, v104
	v_lshl_add_u64 v[46:47], v[46:47], 0, s[0:1]
	v_lshl_add_u64 v[64:65], v[64:65], 0, s[0:1]
	v_lshl_add_u64 v[66:67], v[66:67], 0, s[0:1]
	v_lshl_add_u64 v[68:69], v[68:69], 0, s[0:1]
	s_mov_b32 s2, 0x1e500000
	v_mul_u32_u24_e32 v229, 0x1e0, v103
	v_add_u32_e32 v229, v229, v104
	v_add_u32_e32 v230, 0x10000, v229
	ds_read_b32 v192, v188 offset:0
	ds_read_b32 v193, v188 offset:1024
	ds_read_b32 v194, v188 offset:2048
	ds_read_b32 v195, v188 offset:3072
	ds_read_b32 v196, v188 offset:4096
	ds_read_b32 v197, v188 offset:5120
	ds_read_b32 v198, v188 offset:6144
	ds_read_b32 v199, v188 offset:7168
	ds_read_b32 v200, v188 offset:8192
	s_waitcnt lgkmcnt(8)
	v_fma_f32 v124, v1, v192, v101
	ds_read_b32 v192, v188 offset:9216
	s_waitcnt lgkmcnt(8)
	v_fmac_f32_e32 v124, v51, v193
	v_fma_f32 v125, v1, v193, v101
	ds_read_b32 v193, v188 offset:10240
	s_waitcnt lgkmcnt(8)
	v_fmac_f32_e32 v124, v72, v194
	v_fmac_f32_e32 v125, v51, v194
	v_fma_f32 v126, v1, v194, v101
	ds_read_b32 v194, v188 offset:11264
	s_waitcnt lgkmcnt(8)
	v_fmac_f32_e32 v124, v73, v195
	v_fmac_f32_e32 v125, v72, v195
	v_fmac_f32_e32 v126, v51, v195
	v_fma_f32 v127, v1, v195, v101
	ds_read_b32 v195, v188 offset:12288
	s_waitcnt lgkmcnt(8)
	v_fmac_f32_e32 v124, v74, v196
	v_fmac_f32_e32 v125, v73, v196
	v_fmac_f32_e32 v126, v72, v196
	v_fmac_f32_e32 v127, v51, v196
	v_fma_f32 v128, v1, v196, v101
	ds_read_b32 v196, v188 offset:13312
	s_waitcnt lgkmcnt(8)
	v_fmac_f32_e32 v124, v75, v197
	v_fmac_f32_e32 v125, v74, v197
	v_fmac_f32_e32 v126, v73, v197
	v_fmac_f32_e32 v127, v72, v197
	v_fmac_f32_e32 v128, v51, v197
	v_fma_f32 v129, v1, v197, v101
	ds_read_b32 v197, v188 offset:14336
	s_waitcnt lgkmcnt(8)
	v_fmac_f32_e32 v124, v76, v198
	v_fmac_f32_e32 v125, v75, v198
	v_fmac_f32_e32 v126, v74, v198
	v_fmac_f32_e32 v127, v73, v198
	v_fmac_f32_e32 v128, v72, v198
	v_fmac_f32_e32 v129, v51, v198
	v_fma_f32 v130, v1, v198, v101
	ds_read_b32 v198, v188 offset:15360
	s_waitcnt lgkmcnt(8)
	v_fmac_f32_e32 v124, v77, v199
	v_fmac_f32_e32 v125, v76, v199
	v_fmac_f32_e32 v126, v75, v199
	v_fmac_f32_e32 v127, v74, v199
	v_fmac_f32_e32 v128, v73, v199
	v_fmac_f32_e32 v129, v72, v199
	v_fmac_f32_e32 v130, v51, v199
	v_fma_f32 v131, v1, v199, v101
	ds_read_b32 v199, v188 offset:16384
	s_waitcnt lgkmcnt(8)
	v_fmac_f32_e32 v124, v78, v200
	v_fmac_f32_e32 v125, v77, v200
	v_fmac_f32_e32 v126, v76, v200
	v_fmac_f32_e32 v127, v75, v200
	v_fmac_f32_e32 v128, v74, v200
	v_fmac_f32_e32 v129, v73, v200
	v_fmac_f32_e32 v130, v72, v200
	v_fmac_f32_e32 v131, v51, v200
	v_fma_f32 v132, v1, v200, v101
	ds_read_b32 v200, v188 offset:17408
	s_waitcnt lgkmcnt(8)
	v_fmac_f32_e32 v124, v79, v192
	v_fmac_f32_e32 v125, v78, v192
	v_fmac_f32_e32 v126, v77, v192
	v_fmac_f32_e32 v127, v76, v192
	v_fmac_f32_e32 v128, v75, v192
	v_fmac_f32_e32 v129, v74, v192
	v_fmac_f32_e32 v130, v73, v192
	v_fmac_f32_e32 v131, v72, v192
	v_fmac_f32_e32 v132, v51, v192
	v_fma_f32 v133, v1, v192, v101
	ds_read_b32 v192, v188 offset:18432
	s_waitcnt lgkmcnt(8)
	v_fmac_f32_e32 v124, v80, v193
	v_fmac_f32_e32 v125, v79, v193
	v_fmac_f32_e32 v126, v78, v193
	v_fmac_f32_e32 v127, v77, v193
	v_fmac_f32_e32 v128, v76, v193
	v_fmac_f32_e32 v129, v75, v193
	v_fmac_f32_e32 v130, v74, v193
	v_fmac_f32_e32 v131, v73, v193
	v_fmac_f32_e32 v132, v72, v193
	v_fmac_f32_e32 v133, v51, v193
	v_fma_f32 v134, v1, v193, v101
	ds_read_b32 v193, v188 offset:19456
	s_waitcnt lgkmcnt(8)
	v_fmac_f32_e32 v124, v81, v194
	v_fmac_f32_e32 v125, v80, v194
	v_fmac_f32_e32 v126, v79, v194
	v_fmac_f32_e32 v127, v78, v194
	v_fmac_f32_e32 v128, v77, v194
	v_fmac_f32_e32 v129, v76, v194
	v_fmac_f32_e32 v130, v75, v194
	v_fmac_f32_e32 v131, v74, v194
	v_fmac_f32_e32 v132, v73, v194
	v_fmac_f32_e32 v133, v72, v194
	v_fmac_f32_e32 v134, v51, v194
	v_fma_f32 v135, v1, v194, v101
	ds_read_b32 v194, v188 offset:20480
	s_waitcnt lgkmcnt(8)
	v_fmac_f32_e32 v124, v82, v195
	v_fmac_f32_e32 v125, v81, v195
	v_fmac_f32_e32 v126, v80, v195
	v_fmac_f32_e32 v127, v79, v195
	v_fmac_f32_e32 v128, v78, v195
	v_fmac_f32_e32 v129, v77, v195
	v_fmac_f32_e32 v130, v76, v195
	v_fmac_f32_e32 v131, v75, v195
	v_fmac_f32_e32 v132, v74, v195
	v_fmac_f32_e32 v133, v73, v195
	v_fmac_f32_e32 v134, v72, v195
	v_fmac_f32_e32 v135, v51, v195
	v_fma_f32 v136, v1, v195, v101
	ds_read_b32 v195, v188 offset:21504
	s_waitcnt lgkmcnt(8)
	v_fmac_f32_e32 v124, v83, v196
	v_fmac_f32_e32 v125, v82, v196
	v_fmac_f32_e32 v126, v81, v196
	v_fmac_f32_e32 v127, v80, v196
	v_fmac_f32_e32 v128, v79, v196
	v_fmac_f32_e32 v129, v78, v196
	v_fmac_f32_e32 v130, v77, v196
	v_fmac_f32_e32 v131, v76, v196
	v_fmac_f32_e32 v132, v75, v196
	v_fmac_f32_e32 v133, v74, v196
	v_fmac_f32_e32 v134, v73, v196
	v_fmac_f32_e32 v135, v72, v196
	v_fmac_f32_e32 v136, v51, v196
	v_fma_f32 v137, v1, v196, v101
	ds_read_b32 v196, v188 offset:22528
	s_waitcnt lgkmcnt(8)
	v_fmac_f32_e32 v124, v84, v197
	v_fmac_f32_e32 v125, v83, v197
	v_fmac_f32_e32 v126, v82, v197
	v_fmac_f32_e32 v127, v81, v197
	v_fmac_f32_e32 v128, v80, v197
	v_fmac_f32_e32 v129, v79, v197
	v_fmac_f32_e32 v130, v78, v197
	v_fmac_f32_e32 v131, v77, v197
	v_fmac_f32_e32 v132, v76, v197
	v_fmac_f32_e32 v133, v75, v197
	v_fmac_f32_e32 v134, v74, v197
	v_fmac_f32_e32 v135, v73, v197
	v_fmac_f32_e32 v136, v72, v197
	v_fmac_f32_e32 v137, v51, v197
	v_fma_f32 v148, v1, v197, v101
	ds_read_b32 v197, v188 offset:23552
	s_waitcnt lgkmcnt(8)
; #define LAS __attribute__((address_space(3)))
;     static __device__ __forceinline__ void run(float (&acc)[32], const float (&wv)[31], const LAS float* U, int rb, int cch) {
;         const float uv = U[ring94(ring94(rb + S)) * 256 + cch];
; #pragma unroll
;         for (int o = 0; o < 32; ++o) { constexpr int dummy = 0; const int kk = S - o + dummy; if (kk >= 0 && kk <= 30) acc[o] += wv[kk] * uv; }
;         ConvStep<S + 1>::run(acc, wv, U, rb, cch);
; __device__ __forceinline__ void conv_loop(unsigned char* ws_, const float* const* in_, int l_, LAS unsigned char* lds, int tid, int bid, int G) {
;     ...
;             float acc[32];
; #pragma unroll
;             for (int o = 0; o < 32; ++o) acc[o] = bias;
;             const int rb = base + 32 * half;
;             ConvStep<0>::run(acc, wv, U, rb, cch);
	v_fmac_f32_e32 v124, v85, v198
	v_fmac_f32_e32 v125, v84, v198
	v_fmac_f32_e32 v126, v83, v198
	v_fmac_f32_e32 v127, v82, v198
	v_fmac_f32_e32 v128, v81, v198
	v_fmac_f32_e32 v129, v80, v198
	v_fmac_f32_e32 v130, v79, v198
	v_fmac_f32_e32 v131, v78, v198
	v_fmac_f32_e32 v132, v77, v198
	v_fmac_f32_e32 v133, v76, v198
	v_fmac_f32_e32 v134, v75, v198
	v_fmac_f32_e32 v135, v74, v198
	v_fmac_f32_e32 v136, v73, v198
	v_fmac_f32_e32 v137, v72, v198
	v_fmac_f32_e32 v148, v51, v198
	v_fma_f32 v149, v1, v198, v101
	ds_read_b32 v198, v188 offset:24576
	s_waitcnt lgkmcnt(8)
	v_fmac_f32_e32 v124, v86, v199
	v_fmac_f32_e32 v125, v85, v199
	v_fmac_f32_e32 v126, v84, v199
	v_fmac_f32_e32 v127, v83, v199
	v_fmac_f32_e32 v128, v82, v199
	v_fmac_f32_e32 v129, v81, v199
	v_fmac_f32_e32 v130, v80, v199
	v_fmac_f32_e32 v131, v79, v199
	v_fmac_f32_e32 v132, v78, v199
	v_fmac_f32_e32 v133, v77, v199
	v_fmac_f32_e32 v134, v76, v199
	v_fmac_f32_e32 v135, v75, v199
	v_fmac_f32_e32 v136, v74, v199
	v_fmac_f32_e32 v137, v73, v199
	v_fmac_f32_e32 v148, v72, v199
	v_fmac_f32_e32 v149, v51, v199
	v_fma_f32 v150, v1, v199, v101
	ds_read_b32 v199, v188 offset:25600
	s_waitcnt lgkmcnt(8)
	v_fmac_f32_e32 v124, v87, v200
	v_fmac_f32_e32 v125, v86, v200
	v_fmac_f32_e32 v126, v85, v200
	v_fmac_f32_e32 v127, v84, v200
	v_fmac_f32_e32 v128, v83, v200
	v_fmac_f32_e32 v129, v82, v200
	v_fmac_f32_e32 v130, v81, v200
	v_fmac_f32_e32 v131, v80, v200
	v_fmac_f32_e32 v132, v79, v200
	v_fmac_f32_e32 v133, v78, v200
	v_fmac_f32_e32 v134, v77, v200
	v_fmac_f32_e32 v135, v76, v200
	v_fmac_f32_e32 v136, v75, v200
	v_fmac_f32_e32 v137, v74, v200
	v_fmac_f32_e32 v148, v73, v200
	v_fmac_f32_e32 v149, v72, v200
	v_fmac_f32_e32 v150, v51, v200
	v_fma_f32 v151, v1, v200, v101
	ds_read_b32 v200, v188 offset:26624
	s_waitcnt lgkmcnt(8)
	v_fmac_f32_e32 v124, v88, v192
	v_fmac_f32_e32 v125, v87, v192
	v_fmac_f32_e32 v126, v86, v192
	v_fmac_f32_e32 v127, v85, v192
	v_fmac_f32_e32 v128, v84, v192
	v_fmac_f32_e32 v129, v83, v192
	v_fmac_f32_e32 v130, v82, v192
	v_fmac_f32_e32 v131, v81, v192
	v_fmac_f32_e32 v132, v80, v192
	v_fmac_f32_e32 v133, v79, v192
	v_fmac_f32_e32 v134, v78, v192
	v_fmac_f32_e32 v135, v77, v192
	v_fmac_f32_e32 v136, v76, v192
	v_fmac_f32_e32 v137, v75, v192
	v_fmac_f32_e32 v148, v74, v192
	v_fmac_f32_e32 v149, v73, v192
	v_fmac_f32_e32 v150, v72, v192
	v_fmac_f32_e32 v151, v51, v192
	v_fma_f32 v152, v1, v192, v101
	ds_read_b32 v192, v188 offset:27648
	s_waitcnt lgkmcnt(8)
	v_fmac_f32_e32 v124, v89, v193
	v_fmac_f32_e32 v125, v88, v193
	v_fmac_f32_e32 v126, v87, v193
	v_fmac_f32_e32 v127, v86, v193
	v_fmac_f32_e32 v128, v85, v193
	v_fmac_f32_e32 v129, v84, v193
	v_fmac_f32_e32 v130, v83, v193
	v_fmac_f32_e32 v131, v82, v193
	v_fmac_f32_e32 v132, v81, v193
	v_fmac_f32_e32 v133, v80, v193
	v_fmac_f32_e32 v134, v79, v193
	v_fmac_f32_e32 v135, v78, v193
	v_fmac_f32_e32 v136, v77, v193
	v_fmac_f32_e32 v137, v76, v193
	v_fmac_f32_e32 v148, v75, v193
	v_fmac_f32_e32 v149, v74, v193
	v_fmac_f32_e32 v150, v73, v193
	v_fmac_f32_e32 v151, v72, v193
	v_fmac_f32_e32 v152, v51, v193
	v_fma_f32 v153, v1, v193, v101
	ds_read_b32 v193, v188 offset:28672
	s_waitcnt lgkmcnt(8)
	v_fmac_f32_e32 v124, v90, v194
	v_fmac_f32_e32 v125, v89, v194
	v_fmac_f32_e32 v126, v88, v194
	v_fmac_f32_e32 v127, v87, v194
	v_fmac_f32_e32 v128, v86, v194
	v_fmac_f32_e32 v129, v85, v194
	v_fmac_f32_e32 v130, v84, v194
	v_fmac_f32_e32 v131, v83, v194
	v_fmac_f32_e32 v132, v82, v194
	v_fmac_f32_e32 v133, v81, v194
	v_fmac_f32_e32 v134, v80, v194
	v_fmac_f32_e32 v135, v79, v194
	v_fmac_f32_e32 v136, v78, v194
	v_fmac_f32_e32 v137, v77, v194
	v_fmac_f32_e32 v148, v76, v194
	v_fmac_f32_e32 v149, v75, v194
	v_fmac_f32_e32 v150, v74, v194
	v_fmac_f32_e32 v151, v73, v194
	v_fmac_f32_e32 v152, v72, v194
	v_fmac_f32_e32 v153, v51, v194
	v_fma_f32 v154, v1, v194, v101
	ds_read_b32 v194, v188 offset:29696
	s_waitcnt lgkmcnt(8)
	v_fmac_f32_e32 v124, v91, v195
	v_fmac_f32_e32 v125, v90, v195
	v_fmac_f32_e32 v126, v89, v195
	v_fmac_f32_e32 v127, v88, v195
	v_fmac_f32_e32 v128, v87, v195
	v_fmac_f32_e32 v129, v86, v195
	v_fmac_f32_e32 v130, v85, v195
	v_fmac_f32_e32 v131, v84, v195
	v_fmac_f32_e32 v132, v83, v195
	v_fmac_f32_e32 v133, v82, v195
	v_fmac_f32_e32 v134, v81, v195
	v_fmac_f32_e32 v135, v80, v195
	v_fmac_f32_e32 v136, v79, v195
	v_fmac_f32_e32 v137, v78, v195
	v_fmac_f32_e32 v148, v77, v195
	v_fmac_f32_e32 v149, v76, v195
	v_fmac_f32_e32 v150, v75, v195
	v_fmac_f32_e32 v151, v74, v195
	v_fmac_f32_e32 v152, v73, v195
	v_fmac_f32_e32 v153, v72, v195
	v_fmac_f32_e32 v154, v51, v195
	v_fma_f32 v155, v1, v195, v101
	ds_read_b32 v195, v188 offset:30720
	s_waitcnt lgkmcnt(8)
	v_fmac_f32_e32 v124, v92, v196
	v_fmac_f32_e32 v125, v91, v196
	v_fmac_f32_e32 v126, v90, v196
	v_fmac_f32_e32 v127, v89, v196
	v_fmac_f32_e32 v128, v88, v196
	v_fmac_f32_e32 v129, v87, v196
	v_fmac_f32_e32 v130, v86, v196
	v_fmac_f32_e32 v131, v85, v196
	v_fmac_f32_e32 v132, v84, v196
	v_fmac_f32_e32 v133, v83, v196
	v_fmac_f32_e32 v134, v82, v196
	v_fmac_f32_e32 v135, v81, v196
	v_fmac_f32_e32 v136, v80, v196
	v_fmac_f32_e32 v137, v79, v196
	v_fmac_f32_e32 v148, v78, v196
	v_fmac_f32_e32 v149, v77, v196
	v_fmac_f32_e32 v150, v76, v196
	v_fmac_f32_e32 v151, v75, v196
	v_fmac_f32_e32 v152, v74, v196
	v_fmac_f32_e32 v153, v73, v196
	v_fmac_f32_e32 v154, v72, v196
	v_fmac_f32_e32 v155, v51, v196
	v_fma_f32 v156, v1, v196, v101
	ds_read_b32 v196, v188 offset:31744
	s_waitcnt lgkmcnt(8)
; #define LAS __attribute__((address_space(3)))
;     static __device__ __forceinline__ void run(float (&acc)[32], const float (&wv)[31], const LAS float* U, int rb, int cch) {
;         const float uv = U[ring94(ring94(rb + S)) * 256 + cch];
; #pragma unroll
;         for (int o = 0; o < 32; ++o) { constexpr int dummy = 0; const int kk = S - o + dummy; if (kk >= 0 && kk <= 30) acc[o] += wv[kk] * uv; }
;         ConvStep<S + 1>::run(acc, wv, U, rb, cch);
; __device__ __forceinline__ void conv_loop(unsigned char* ws_, const float* const* in_, int l_, LAS unsigned char* lds, int tid, int bid, int G) {
;     ...
;             float acc[32];
; #pragma unroll
;             for (int o = 0; o < 32; ++o) acc[o] = bias;
;             const int rb = base + 32 * half;
;             ConvStep<0>::run(acc, wv, U, rb, cch);
	v_fmac_f32_e32 v124, v93, v197
	v_fmac_f32_e32 v125, v92, v197
	v_fmac_f32_e32 v126, v91, v197
	v_fmac_f32_e32 v127, v90, v197
	v_fmac_f32_e32 v128, v89, v197
	v_fmac_f32_e32 v129, v88, v197
	v_fmac_f32_e32 v130, v87, v197
	v_fmac_f32_e32 v131, v86, v197
	v_fmac_f32_e32 v132, v85, v197
	v_fmac_f32_e32 v133, v84, v197
	v_fmac_f32_e32 v134, v83, v197
	v_fmac_f32_e32 v135, v82, v197
	v_fmac_f32_e32 v136, v81, v197
	v_fmac_f32_e32 v137, v80, v197
	v_fmac_f32_e32 v148, v79, v197
	v_fmac_f32_e32 v149, v78, v197
	v_fmac_f32_e32 v150, v77, v197
	v_fmac_f32_e32 v151, v76, v197
	v_fmac_f32_e32 v152, v75, v197
	v_fmac_f32_e32 v153, v74, v197
	v_fmac_f32_e32 v154, v73, v197
	v_fmac_f32_e32 v155, v72, v197
	v_fmac_f32_e32 v156, v51, v197
	v_fma_f32 v157, v1, v197, v101
	ds_read_b32 v197, v188 offset:32768
	s_waitcnt lgkmcnt(8)
	v_fmac_f32_e32 v124, v94, v198
	v_fmac_f32_e32 v125, v93, v198
	v_fmac_f32_e32 v126, v92, v198
	v_fmac_f32_e32 v127, v91, v198
	v_fmac_f32_e32 v128, v90, v198
	v_fmac_f32_e32 v129, v89, v198
	v_fmac_f32_e32 v130, v88, v198
	v_fmac_f32_e32 v131, v87, v198
	v_fmac_f32_e32 v132, v86, v198
	v_fmac_f32_e32 v133, v85, v198
	v_fmac_f32_e32 v134, v84, v198
	v_fmac_f32_e32 v135, v83, v198
	v_fmac_f32_e32 v136, v82, v198
	v_fmac_f32_e32 v137, v81, v198
	v_fmac_f32_e32 v148, v80, v198
	v_fmac_f32_e32 v149, v79, v198
	v_fmac_f32_e32 v150, v78, v198
	v_fmac_f32_e32 v151, v77, v198
	v_fmac_f32_e32 v152, v76, v198
	v_fmac_f32_e32 v153, v75, v198
	v_fmac_f32_e32 v154, v74, v198
	v_fmac_f32_e32 v155, v73, v198
	v_fmac_f32_e32 v156, v72, v198
	v_fmac_f32_e32 v157, v51, v198
	v_fma_f32 v158, v1, v198, v101
	ds_read_b32 v198, v188 offset:33792
	s_waitcnt lgkmcnt(8)
	v_fmac_f32_e32 v124, v95, v199
	v_fmac_f32_e32 v125, v94, v199
	v_fmac_f32_e32 v126, v93, v199
	v_fmac_f32_e32 v127, v92, v199
	v_fmac_f32_e32 v128, v91, v199
	v_fmac_f32_e32 v129, v90, v199
	v_fmac_f32_e32 v130, v89, v199
	v_fmac_f32_e32 v131, v88, v199
	v_fmac_f32_e32 v132, v87, v199
	v_fmac_f32_e32 v133, v86, v199
	v_fmac_f32_e32 v134, v85, v199
	v_fmac_f32_e32 v135, v84, v199
	v_fmac_f32_e32 v136, v83, v199
	v_fmac_f32_e32 v137, v82, v199
	v_fmac_f32_e32 v148, v81, v199
	v_fmac_f32_e32 v149, v80, v199
	v_fmac_f32_e32 v150, v79, v199
	v_fmac_f32_e32 v151, v78, v199
	v_fmac_f32_e32 v152, v77, v199
	v_fmac_f32_e32 v153, v76, v199
	v_fmac_f32_e32 v154, v75, v199
	v_fmac_f32_e32 v155, v74, v199
	v_fmac_f32_e32 v156, v73, v199
	v_fmac_f32_e32 v157, v72, v199
	v_fmac_f32_e32 v158, v51, v199
	v_fma_f32 v159, v1, v199, v101
	ds_read_b32 v199, v188 offset:34816
	s_waitcnt lgkmcnt(8)
	v_fmac_f32_e32 v124, v96, v200
	v_fmac_f32_e32 v125, v95, v200
	v_fmac_f32_e32 v126, v94, v200
	v_fmac_f32_e32 v127, v93, v200
	v_fmac_f32_e32 v128, v92, v200
	v_fmac_f32_e32 v129, v91, v200
	v_fmac_f32_e32 v130, v90, v200
	v_fmac_f32_e32 v131, v89, v200
	v_fmac_f32_e32 v132, v88, v200
	v_fmac_f32_e32 v133, v87, v200
	v_fmac_f32_e32 v134, v86, v200
	v_fmac_f32_e32 v135, v85, v200
	v_fmac_f32_e32 v136, v84, v200
	v_fmac_f32_e32 v137, v83, v200
	v_fmac_f32_e32 v148, v82, v200
	v_fmac_f32_e32 v149, v81, v200
	v_fmac_f32_e32 v150, v80, v200
	v_fmac_f32_e32 v151, v79, v200
	v_fmac_f32_e32 v152, v78, v200
	v_fmac_f32_e32 v153, v77, v200
	v_fmac_f32_e32 v154, v76, v200
	v_fmac_f32_e32 v155, v75, v200
	v_fmac_f32_e32 v156, v74, v200
	v_fmac_f32_e32 v157, v73, v200
	v_fmac_f32_e32 v158, v72, v200
	v_fmac_f32_e32 v159, v51, v200
	v_fma_f32 v160, v1, v200, v101
	ds_read_b32 v200, v188 offset:35840
	s_waitcnt lgkmcnt(8)
	v_fmac_f32_e32 v124, v97, v192
	v_fmac_f32_e32 v125, v96, v192
	v_fmac_f32_e32 v126, v95, v192
	v_fmac_f32_e32 v127, v94, v192
	v_fmac_f32_e32 v128, v93, v192
	v_fmac_f32_e32 v129, v92, v192
	v_fmac_f32_e32 v130, v91, v192
	v_fmac_f32_e32 v131, v90, v192
	v_fmac_f32_e32 v132, v89, v192
	v_fmac_f32_e32 v133, v88, v192
	v_fmac_f32_e32 v134, v87, v192
	v_fmac_f32_e32 v135, v86, v192
	v_fmac_f32_e32 v136, v85, v192
	v_fmac_f32_e32 v137, v84, v192
	v_fmac_f32_e32 v148, v83, v192
	v_fmac_f32_e32 v149, v82, v192
	v_fmac_f32_e32 v150, v81, v192
	v_fmac_f32_e32 v151, v80, v192
	v_fmac_f32_e32 v152, v79, v192
	v_fmac_f32_e32 v153, v78, v192
	v_fmac_f32_e32 v154, v77, v192
	v_fmac_f32_e32 v155, v76, v192
	v_fmac_f32_e32 v156, v75, v192
	v_fmac_f32_e32 v157, v74, v192
	v_fmac_f32_e32 v158, v73, v192
	v_fmac_f32_e32 v159, v72, v192
	v_fmac_f32_e32 v160, v51, v192
	v_fma_f32 v161, v1, v192, v101
	ds_read_b32 v192, v188 offset:36864
	s_waitcnt lgkmcnt(8)
	v_fmac_f32_e32 v124, v98, v193
	v_fmac_f32_e32 v125, v97, v193
	v_fmac_f32_e32 v126, v96, v193
	v_fmac_f32_e32 v127, v95, v193
	v_fmac_f32_e32 v128, v94, v193
	v_fmac_f32_e32 v129, v93, v193
	v_fmac_f32_e32 v130, v92, v193
	v_fmac_f32_e32 v131, v91, v193
	v_fmac_f32_e32 v132, v90, v193
	v_fmac_f32_e32 v133, v89, v193
	v_fmac_f32_e32 v134, v88, v193
	v_fmac_f32_e32 v135, v87, v193
	v_fmac_f32_e32 v136, v86, v193
	v_fmac_f32_e32 v137, v85, v193
	v_fmac_f32_e32 v148, v84, v193
	v_fmac_f32_e32 v149, v83, v193
	v_fmac_f32_e32 v150, v82, v193
	v_fmac_f32_e32 v151, v81, v193
	v_fmac_f32_e32 v152, v80, v193
	v_fmac_f32_e32 v153, v79, v193
	v_fmac_f32_e32 v154, v78, v193
	v_fmac_f32_e32 v155, v77, v193
	v_fmac_f32_e32 v156, v76, v193
	v_fmac_f32_e32 v157, v75, v193
	v_fmac_f32_e32 v158, v74, v193
	v_fmac_f32_e32 v159, v73, v193
	v_fmac_f32_e32 v160, v72, v193
	v_fmac_f32_e32 v161, v51, v193
	v_fma_f32 v162, v1, v193, v101
	ds_read_b32 v193, v188 offset:37888
	s_waitcnt lgkmcnt(8)
; #define LAS __attribute__((address_space(3)))
;     static __device__ __forceinline__ void run(float (&acc)[32], const float (&wv)[31], const LAS float* U, int rb, int cch) {
;         const float uv = U[ring94(ring94(rb + S)) * 256 + cch];
; #pragma unroll
;         for (int o = 0; o < 32; ++o) { constexpr int dummy = 0; const int kk = S - o + dummy; if (kk >= 0 && kk <= 30) acc[o] += wv[kk] * uv; }
;         ConvStep<S + 1>::run(acc, wv, U, rb, cch);
; __device__ __forceinline__ void conv_loop(unsigned char* ws_, const float* const* in_, int l_, LAS unsigned char* lds, int tid, int bid, int G) {
;     ...
;             float acc[32];
; #pragma unroll
;             for (int o = 0; o < 32; ++o) acc[o] = bias;
;             const int rb = base + 32 * half;
;             ConvStep<0>::run(acc, wv, U, rb, cch);
	v_fmac_f32_e32 v124, v99, v194
	v_fmac_f32_e32 v125, v98, v194
	v_fmac_f32_e32 v126, v97, v194
	v_fmac_f32_e32 v127, v96, v194
	v_fmac_f32_e32 v128, v95, v194
	v_fmac_f32_e32 v129, v94, v194
	v_fmac_f32_e32 v130, v93, v194
	v_fmac_f32_e32 v131, v92, v194
	v_fmac_f32_e32 v132, v91, v194
	v_fmac_f32_e32 v133, v90, v194
	v_fmac_f32_e32 v134, v89, v194
	v_fmac_f32_e32 v135, v88, v194
	v_fmac_f32_e32 v136, v87, v194
	v_fmac_f32_e32 v137, v86, v194
	v_fmac_f32_e32 v148, v85, v194
	v_fmac_f32_e32 v149, v84, v194
	v_fmac_f32_e32 v150, v83, v194
	v_fmac_f32_e32 v151, v82, v194
	v_fmac_f32_e32 v152, v81, v194
	v_fmac_f32_e32 v153, v80, v194
	v_fmac_f32_e32 v154, v79, v194
	v_fmac_f32_e32 v155, v78, v194
	v_fmac_f32_e32 v156, v77, v194
	v_fmac_f32_e32 v157, v76, v194
	v_fmac_f32_e32 v158, v75, v194
	v_fmac_f32_e32 v159, v74, v194
	v_fmac_f32_e32 v160, v73, v194
	v_fmac_f32_e32 v161, v72, v194
	v_fmac_f32_e32 v162, v51, v194
	v_fma_f32 v163, v1, v194, v101
	ds_read_b32 v194, v188 offset:38912
	s_waitcnt lgkmcnt(8)
	v_fmac_f32_e32 v124, v100, v195
	v_fmac_f32_e32 v125, v99, v195
	v_fmac_f32_e32 v126, v98, v195
	v_fmac_f32_e32 v127, v97, v195
	v_fmac_f32_e32 v128, v96, v195
	v_fmac_f32_e32 v129, v95, v195
	v_fmac_f32_e32 v130, v94, v195
	v_fmac_f32_e32 v131, v93, v195
	v_fmac_f32_e32 v132, v92, v195
	v_fmac_f32_e32 v133, v91, v195
	v_fmac_f32_e32 v134, v90, v195
	v_fmac_f32_e32 v135, v89, v195
	v_fmac_f32_e32 v136, v88, v195
	v_fmac_f32_e32 v137, v87, v195
	v_fmac_f32_e32 v148, v86, v195
	v_fmac_f32_e32 v149, v85, v195
	v_fmac_f32_e32 v150, v84, v195
	v_fmac_f32_e32 v151, v83, v195
	v_fmac_f32_e32 v152, v82, v195
	v_fmac_f32_e32 v153, v81, v195
	v_fmac_f32_e32 v154, v80, v195
	v_fmac_f32_e32 v155, v79, v195
	v_fmac_f32_e32 v156, v78, v195
	v_fmac_f32_e32 v157, v77, v195
	v_fmac_f32_e32 v158, v76, v195
	v_fmac_f32_e32 v159, v75, v195
	v_fmac_f32_e32 v160, v74, v195
	v_fmac_f32_e32 v161, v73, v195
	v_fmac_f32_e32 v162, v72, v195
	v_fmac_f32_e32 v163, v51, v195
	v_fma_f32 v164, v1, v195, v101
	ds_read_b32 v195, v188 offset:39936
	s_waitcnt lgkmcnt(8)
	v_fmac_f32_e32 v125, v100, v196
	v_fmac_f32_e32 v126, v99, v196
	v_fmac_f32_e32 v127, v98, v196
	v_fmac_f32_e32 v128, v97, v196
	v_fmac_f32_e32 v129, v96, v196
	v_fmac_f32_e32 v130, v95, v196
	v_fmac_f32_e32 v131, v94, v196
	v_fmac_f32_e32 v132, v93, v196
	v_fmac_f32_e32 v133, v92, v196
	v_fmac_f32_e32 v134, v91, v196
	v_fmac_f32_e32 v135, v90, v196
	v_fmac_f32_e32 v136, v89, v196
	v_fmac_f32_e32 v137, v88, v196
	v_fmac_f32_e32 v148, v87, v196
	v_fmac_f32_e32 v149, v86, v196
	v_fmac_f32_e32 v150, v85, v196
	v_fmac_f32_e32 v151, v84, v196
	v_fmac_f32_e32 v152, v83, v196
	v_fmac_f32_e32 v153, v82, v196
	v_fmac_f32_e32 v154, v81, v196
	v_fmac_f32_e32 v155, v80, v196
	v_fmac_f32_e32 v156, v79, v196
	v_fmac_f32_e32 v157, v78, v196
	v_fmac_f32_e32 v158, v77, v196
	v_fmac_f32_e32 v159, v76, v196
	v_fmac_f32_e32 v160, v75, v196
	v_fmac_f32_e32 v161, v74, v196
	v_fmac_f32_e32 v162, v73, v196
	v_fmac_f32_e32 v163, v72, v196
	v_fmac_f32_e32 v164, v51, v196
	v_fma_f32 v165, v1, v196, v101
	ds_read_b32 v196, v188 offset:40960
	s_waitcnt lgkmcnt(8)
	v_fmac_f32_e32 v126, v100, v197
	v_fmac_f32_e32 v127, v99, v197
	v_fmac_f32_e32 v128, v98, v197
	v_fmac_f32_e32 v129, v97, v197
	v_fmac_f32_e32 v130, v96, v197
	v_fmac_f32_e32 v131, v95, v197
	v_fmac_f32_e32 v132, v94, v197
	v_fmac_f32_e32 v133, v93, v197
	v_fmac_f32_e32 v134, v92, v197
	v_fmac_f32_e32 v135, v91, v197
	v_fmac_f32_e32 v136, v90, v197
	v_fmac_f32_e32 v137, v89, v197
	v_fmac_f32_e32 v148, v88, v197
	v_fmac_f32_e32 v149, v87, v197
	v_fmac_f32_e32 v150, v86, v197
	v_fmac_f32_e32 v151, v85, v197
	v_fmac_f32_e32 v152, v84, v197
	v_fmac_f32_e32 v153, v83, v197
	v_fmac_f32_e32 v154, v82, v197
	v_fmac_f32_e32 v155, v81, v197
	v_fmac_f32_e32 v156, v80, v197
	v_fmac_f32_e32 v157, v79, v197
	v_fmac_f32_e32 v158, v78, v197
	v_fmac_f32_e32 v159, v77, v197
	v_fmac_f32_e32 v160, v76, v197
	v_fmac_f32_e32 v161, v75, v197
	v_fmac_f32_e32 v162, v74, v197
	v_fmac_f32_e32 v163, v73, v197
	v_fmac_f32_e32 v164, v72, v197
	v_fmac_f32_e32 v165, v51, v197
	ds_read_b32 v197, v188 offset:41984
	s_waitcnt lgkmcnt(8)
	v_fmac_f32_e32 v127, v100, v198
	v_fmac_f32_e32 v128, v99, v198
	v_fmac_f32_e32 v129, v98, v198
	v_fmac_f32_e32 v130, v97, v198
	v_fmac_f32_e32 v131, v96, v198
	v_fmac_f32_e32 v132, v95, v198
	v_fmac_f32_e32 v133, v94, v198
	v_fmac_f32_e32 v134, v93, v198
	v_fmac_f32_e32 v135, v92, v198
	v_fmac_f32_e32 v136, v91, v198
	v_fmac_f32_e32 v137, v90, v198
	v_fmac_f32_e32 v148, v89, v198
	v_fmac_f32_e32 v149, v88, v198
	v_fmac_f32_e32 v150, v87, v198
	v_fmac_f32_e32 v151, v86, v198
	v_fmac_f32_e32 v152, v85, v198
	v_fmac_f32_e32 v153, v84, v198
	v_fmac_f32_e32 v154, v83, v198
	v_fmac_f32_e32 v155, v82, v198
	v_fmac_f32_e32 v156, v81, v198
	v_fmac_f32_e32 v157, v80, v198
	v_fmac_f32_e32 v158, v79, v198
	v_fmac_f32_e32 v159, v78, v198
	v_fmac_f32_e32 v160, v77, v198
	v_fmac_f32_e32 v161, v76, v198
	v_fmac_f32_e32 v162, v75, v198
	v_fmac_f32_e32 v163, v74, v198
	v_fmac_f32_e32 v164, v73, v198
	v_fmac_f32_e32 v165, v72, v198
	ds_read_b32 v198, v188 offset:43008
	s_waitcnt lgkmcnt(8)
	v_fmac_f32_e32 v128, v100, v199
	v_fmac_f32_e32 v129, v99, v199
	v_fmac_f32_e32 v130, v98, v199
	v_fmac_f32_e32 v131, v97, v199
	v_fmac_f32_e32 v132, v96, v199
	v_fmac_f32_e32 v133, v95, v199
	v_fmac_f32_e32 v134, v94, v199
	v_fmac_f32_e32 v135, v93, v199
	v_fmac_f32_e32 v136, v92, v199
	v_fmac_f32_e32 v137, v91, v199
	v_fmac_f32_e32 v148, v90, v199
	v_fmac_f32_e32 v149, v89, v199
	v_fmac_f32_e32 v150, v88, v199
	v_fmac_f32_e32 v151, v87, v199
	v_fmac_f32_e32 v152, v86, v199
	v_fmac_f32_e32 v153, v85, v199
	v_fmac_f32_e32 v154, v84, v199
	v_fmac_f32_e32 v155, v83, v199
	v_fmac_f32_e32 v156, v82, v199
	v_fmac_f32_e32 v157, v81, v199
	v_fmac_f32_e32 v158, v80, v199
	v_fmac_f32_e32 v159, v79, v199
	v_fmac_f32_e32 v160, v78, v199
	v_fmac_f32_e32 v161, v77, v199
	v_fmac_f32_e32 v162, v76, v199
	v_fmac_f32_e32 v163, v75, v199
	v_fmac_f32_e32 v164, v74, v199
	v_fmac_f32_e32 v165, v73, v199
	ds_read_b32 v199, v188 offset:44032
	s_waitcnt lgkmcnt(8)
; #define LAS __attribute__((address_space(3)))
;     static __device__ __forceinline__ void run(float (&acc)[32], const float (&wv)[31], const LAS float* U, int rb, int cch) {
;         const float uv = U[ring94(ring94(rb + S)) * 256 + cch];
; #pragma unroll
;         for (int o = 0; o < 32; ++o) { constexpr int dummy = 0; const int kk = S - o + dummy; if (kk >= 0 && kk <= 30) acc[o] += wv[kk] * uv; }
;         ConvStep<S + 1>::run(acc, wv, U, rb, cch);
; __device__ __forceinline__ void conv_loop(unsigned char* ws_, const float* const* in_, int l_, LAS unsigned char* lds, int tid, int bid, int G) {
;     ...
;             float acc[32];
; #pragma unroll
;             for (int o = 0; o < 32; ++o) acc[o] = bias;
;             const int rb = base + 32 * half;
;             ConvStep<0>::run(acc, wv, U, rb, cch);
	v_fmac_f32_e32 v129, v100, v200
	v_fmac_f32_e32 v130, v99, v200
	v_fmac_f32_e32 v131, v98, v200
	v_fmac_f32_e32 v132, v97, v200
	v_fmac_f32_e32 v133, v96, v200
	v_fmac_f32_e32 v134, v95, v200
	v_fmac_f32_e32 v135, v94, v200
	v_fmac_f32_e32 v136, v93, v200
	v_fmac_f32_e32 v137, v92, v200
	v_fmac_f32_e32 v148, v91, v200
	v_fmac_f32_e32 v149, v90, v200
	v_fmac_f32_e32 v150, v89, v200
	v_fmac_f32_e32 v151, v88, v200
	v_fmac_f32_e32 v152, v87, v200
	v_fmac_f32_e32 v153, v86, v200
	v_fmac_f32_e32 v154, v85, v200
	v_fmac_f32_e32 v155, v84, v200
	v_fmac_f32_e32 v156, v83, v200
	v_fmac_f32_e32 v157, v82, v200
	v_fmac_f32_e32 v158, v81, v200
	v_fmac_f32_e32 v159, v80, v200
	v_fmac_f32_e32 v160, v79, v200
	v_fmac_f32_e32 v161, v78, v200
	v_fmac_f32_e32 v162, v77, v200
	v_fmac_f32_e32 v163, v76, v200
	v_fmac_f32_e32 v164, v75, v200
	v_fmac_f32_e32 v165, v74, v200
	ds_read_b32 v200, v188 offset:45056
	s_waitcnt lgkmcnt(8)
	v_fmac_f32_e32 v130, v100, v192
	v_fmac_f32_e32 v131, v99, v192
	v_fmac_f32_e32 v132, v98, v192
	v_fmac_f32_e32 v133, v97, v192
	v_fmac_f32_e32 v134, v96, v192
	v_fmac_f32_e32 v135, v95, v192
	v_fmac_f32_e32 v136, v94, v192
	v_fmac_f32_e32 v137, v93, v192
	v_fmac_f32_e32 v148, v92, v192
	v_fmac_f32_e32 v149, v91, v192
	v_fmac_f32_e32 v150, v90, v192
	v_fmac_f32_e32 v151, v89, v192
	v_fmac_f32_e32 v152, v88, v192
	v_fmac_f32_e32 v153, v87, v192
	v_fmac_f32_e32 v154, v86, v192
	v_fmac_f32_e32 v155, v85, v192
	v_fmac_f32_e32 v156, v84, v192
	v_fmac_f32_e32 v157, v83, v192
	v_fmac_f32_e32 v158, v82, v192
	v_fmac_f32_e32 v159, v81, v192
	v_fmac_f32_e32 v160, v80, v192
	v_fmac_f32_e32 v161, v79, v192
	v_fmac_f32_e32 v162, v78, v192
	v_fmac_f32_e32 v163, v77, v192
	v_fmac_f32_e32 v164, v76, v192
	v_fmac_f32_e32 v165, v75, v192
	ds_read_b32 v192, v188 offset:46080
	s_waitcnt lgkmcnt(8)
	v_fmac_f32_e32 v131, v100, v193
	v_fmac_f32_e32 v132, v99, v193
	v_fmac_f32_e32 v133, v98, v193
	v_fmac_f32_e32 v134, v97, v193
	v_fmac_f32_e32 v135, v96, v193
	v_fmac_f32_e32 v136, v95, v193
	v_fmac_f32_e32 v137, v94, v193
	v_fmac_f32_e32 v148, v93, v193
	v_fmac_f32_e32 v149, v92, v193
	v_fmac_f32_e32 v150, v91, v193
	v_fmac_f32_e32 v151, v90, v193
	v_fmac_f32_e32 v152, v89, v193
	v_fmac_f32_e32 v153, v88, v193
	v_fmac_f32_e32 v154, v87, v193
	v_fmac_f32_e32 v155, v86, v193
	v_fmac_f32_e32 v156, v85, v193
	v_fmac_f32_e32 v157, v84, v193
	v_fmac_f32_e32 v158, v83, v193
	v_fmac_f32_e32 v159, v82, v193
	v_fmac_f32_e32 v160, v81, v193
	v_fmac_f32_e32 v161, v80, v193
	v_fmac_f32_e32 v162, v79, v193
	v_fmac_f32_e32 v163, v78, v193
	v_fmac_f32_e32 v164, v77, v193
	v_fmac_f32_e32 v165, v76, v193
	ds_read_b32 v193, v188 offset:47104
	s_waitcnt lgkmcnt(8)
	v_fmac_f32_e32 v132, v100, v194
	v_fmac_f32_e32 v133, v99, v194
	v_fmac_f32_e32 v134, v98, v194
	v_fmac_f32_e32 v135, v97, v194
	v_fmac_f32_e32 v136, v96, v194
	v_fmac_f32_e32 v137, v95, v194
	v_fmac_f32_e32 v148, v94, v194
	v_fmac_f32_e32 v149, v93, v194
	v_fmac_f32_e32 v150, v92, v194
	v_fmac_f32_e32 v151, v91, v194
	v_fmac_f32_e32 v152, v90, v194
	v_fmac_f32_e32 v153, v89, v194
	v_fmac_f32_e32 v154, v88, v194
	v_fmac_f32_e32 v155, v87, v194
	v_fmac_f32_e32 v156, v86, v194
	v_fmac_f32_e32 v157, v85, v194
	v_fmac_f32_e32 v158, v84, v194
	v_fmac_f32_e32 v159, v83, v194
	v_fmac_f32_e32 v160, v82, v194
	v_fmac_f32_e32 v161, v81, v194
	v_fmac_f32_e32 v162, v80, v194
	v_fmac_f32_e32 v163, v79, v194
	v_fmac_f32_e32 v164, v78, v194
	v_fmac_f32_e32 v165, v77, v194
	ds_read_b32 v194, v188 offset:48128
	s_waitcnt lgkmcnt(8)
	v_fmac_f32_e32 v133, v100, v195
	v_fmac_f32_e32 v134, v99, v195
	v_fmac_f32_e32 v135, v98, v195
	v_fmac_f32_e32 v136, v97, v195
	v_fmac_f32_e32 v137, v96, v195
	v_fmac_f32_e32 v148, v95, v195
	v_fmac_f32_e32 v149, v94, v195
	v_fmac_f32_e32 v150, v93, v195
	v_fmac_f32_e32 v151, v92, v195
	v_fmac_f32_e32 v152, v91, v195
	v_fmac_f32_e32 v153, v90, v195
	v_fmac_f32_e32 v154, v89, v195
	v_fmac_f32_e32 v155, v88, v195
	v_fmac_f32_e32 v156, v87, v195
	v_fmac_f32_e32 v157, v86, v195
	v_fmac_f32_e32 v158, v85, v195
	v_fmac_f32_e32 v159, v84, v195
	v_fmac_f32_e32 v160, v83, v195
	v_fmac_f32_e32 v161, v82, v195
	v_fmac_f32_e32 v162, v81, v195
	v_fmac_f32_e32 v163, v80, v195
	v_fmac_f32_e32 v164, v79, v195
	v_fmac_f32_e32 v165, v78, v195
	ds_read_b32 v195, v188 offset:49152
	s_waitcnt lgkmcnt(8)
	v_fmac_f32_e32 v134, v100, v196
	v_fmac_f32_e32 v135, v99, v196
	v_fmac_f32_e32 v136, v98, v196
	v_fmac_f32_e32 v137, v97, v196
	v_fmac_f32_e32 v148, v96, v196
	v_fmac_f32_e32 v149, v95, v196
	v_fmac_f32_e32 v150, v94, v196
	v_fmac_f32_e32 v151, v93, v196
	v_fmac_f32_e32 v152, v92, v196
	v_fmac_f32_e32 v153, v91, v196
	v_fmac_f32_e32 v154, v90, v196
	v_fmac_f32_e32 v155, v89, v196
	v_fmac_f32_e32 v156, v88, v196
	v_fmac_f32_e32 v157, v87, v196
	v_fmac_f32_e32 v158, v86, v196
	v_fmac_f32_e32 v159, v85, v196
	v_fmac_f32_e32 v160, v84, v196
	v_fmac_f32_e32 v161, v83, v196
	v_fmac_f32_e32 v162, v82, v196
	v_fmac_f32_e32 v163, v81, v196
	v_fmac_f32_e32 v164, v80, v196
	v_fmac_f32_e32 v165, v79, v196
	ds_read_b32 v196, v188 offset:50176
	s_waitcnt lgkmcnt(8)
	v_fmac_f32_e32 v135, v100, v197
	v_fmac_f32_e32 v136, v99, v197
	v_fmac_f32_e32 v137, v98, v197
	v_fmac_f32_e32 v148, v97, v197
	v_fmac_f32_e32 v149, v96, v197
	v_fmac_f32_e32 v150, v95, v197
	v_fmac_f32_e32 v151, v94, v197
	v_fmac_f32_e32 v152, v93, v197
	v_fmac_f32_e32 v153, v92, v197
	v_fmac_f32_e32 v154, v91, v197
	v_fmac_f32_e32 v155, v90, v197
	v_fmac_f32_e32 v156, v89, v197
	v_fmac_f32_e32 v157, v88, v197
	v_fmac_f32_e32 v158, v87, v197
	v_fmac_f32_e32 v159, v86, v197
	v_fmac_f32_e32 v160, v85, v197
	v_fmac_f32_e32 v161, v84, v197
	v_fmac_f32_e32 v162, v83, v197
	v_fmac_f32_e32 v163, v82, v197
	v_fmac_f32_e32 v164, v81, v197
	v_fmac_f32_e32 v165, v80, v197
	ds_read_b32 v197, v188 offset:51200
	s_waitcnt lgkmcnt(8)
; #define LAS __attribute__((address_space(3)))
;     static __device__ __forceinline__ void run(float (&acc)[32], const float (&wv)[31], const LAS float* U, int rb, int cch) {
;         const float uv = U[ring94(ring94(rb + S)) * 256 + cch];
; #pragma unroll
;         for (int o = 0; o < 32; ++o) { constexpr int dummy = 0; const int kk = S - o + dummy; if (kk >= 0 && kk <= 30) acc[o] += wv[kk] * uv; }
;         ConvStep<S + 1>::run(acc, wv, U, rb, cch);
; __device__ __forceinline__ void conv_loop(unsigned char* ws_, const float* const* in_, int l_, LAS unsigned char* lds, int tid, int bid, int G) {
;     ...
;             float acc[32];
; #pragma unroll
;             for (int o = 0; o < 32; ++o) acc[o] = bias;
;             const int rb = base + 32 * half;
;             ConvStep<0>::run(acc, wv, U, rb, cch);
	v_fmac_f32_e32 v136, v100, v198
	v_fmac_f32_e32 v137, v99, v198
	v_fmac_f32_e32 v148, v98, v198
	v_fmac_f32_e32 v149, v97, v198
	v_fmac_f32_e32 v150, v96, v198
	v_fmac_f32_e32 v151, v95, v198
	v_fmac_f32_e32 v152, v94, v198
	v_fmac_f32_e32 v153, v93, v198
	v_fmac_f32_e32 v154, v92, v198
	v_fmac_f32_e32 v155, v91, v198
	v_fmac_f32_e32 v156, v90, v198
	v_fmac_f32_e32 v157, v89, v198
	v_fmac_f32_e32 v158, v88, v198
	v_fmac_f32_e32 v159, v87, v198
	v_fmac_f32_e32 v160, v86, v198
	v_fmac_f32_e32 v161, v85, v198
	v_fmac_f32_e32 v162, v84, v198
	v_fmac_f32_e32 v163, v83, v198
	v_fmac_f32_e32 v164, v82, v198
	v_fmac_f32_e32 v165, v81, v198
	ds_read_b32 v198, v188 offset:52224
	s_waitcnt lgkmcnt(8)
	v_fmac_f32_e32 v137, v100, v199
	v_fmac_f32_e32 v148, v99, v199
	v_fmac_f32_e32 v149, v98, v199
	v_fmac_f32_e32 v150, v97, v199
	v_fmac_f32_e32 v151, v96, v199
	v_fmac_f32_e32 v152, v95, v199
	v_fmac_f32_e32 v153, v94, v199
	v_fmac_f32_e32 v154, v93, v199
	v_fmac_f32_e32 v155, v92, v199
	v_fmac_f32_e32 v156, v91, v199
	v_fmac_f32_e32 v157, v90, v199
	v_fmac_f32_e32 v158, v89, v199
	v_fmac_f32_e32 v159, v88, v199
	v_fmac_f32_e32 v160, v87, v199
	v_fmac_f32_e32 v161, v86, v199
	v_fmac_f32_e32 v162, v85, v199
	v_fmac_f32_e32 v163, v84, v199
	v_fmac_f32_e32 v164, v83, v199
	v_fmac_f32_e32 v165, v82, v199
	ds_read_b32 v199, v188 offset:53248
	s_waitcnt lgkmcnt(8)
	v_fmac_f32_e32 v148, v100, v200
	v_fmac_f32_e32 v149, v99, v200
	v_fmac_f32_e32 v150, v98, v200
	v_fmac_f32_e32 v151, v97, v200
	v_fmac_f32_e32 v152, v96, v200
	v_fmac_f32_e32 v153, v95, v200
	v_fmac_f32_e32 v154, v94, v200
	v_fmac_f32_e32 v155, v93, v200
	v_fmac_f32_e32 v156, v92, v200
	v_fmac_f32_e32 v157, v91, v200
	v_fmac_f32_e32 v158, v90, v200
	v_fmac_f32_e32 v159, v89, v200
	v_fmac_f32_e32 v160, v88, v200
	v_fmac_f32_e32 v161, v87, v200
	v_fmac_f32_e32 v162, v86, v200
	v_fmac_f32_e32 v163, v85, v200
	v_fmac_f32_e32 v164, v84, v200
	v_fmac_f32_e32 v165, v83, v200
	ds_read_b32 v200, v188 offset:54272
	s_waitcnt lgkmcnt(8)
	v_fmac_f32_e32 v149, v100, v192
	v_fmac_f32_e32 v150, v99, v192
	v_fmac_f32_e32 v151, v98, v192
	v_fmac_f32_e32 v152, v97, v192
	v_fmac_f32_e32 v153, v96, v192
	v_fmac_f32_e32 v154, v95, v192
	v_fmac_f32_e32 v155, v94, v192
	v_fmac_f32_e32 v156, v93, v192
	v_fmac_f32_e32 v157, v92, v192
	v_fmac_f32_e32 v158, v91, v192
	v_fmac_f32_e32 v159, v90, v192
	v_fmac_f32_e32 v160, v89, v192
	v_fmac_f32_e32 v161, v88, v192
	v_fmac_f32_e32 v162, v87, v192
	v_fmac_f32_e32 v163, v86, v192
	v_fmac_f32_e32 v164, v85, v192
	v_fmac_f32_e32 v165, v84, v192
	ds_read_b32 v192, v188 offset:55296
	s_waitcnt lgkmcnt(8)
	v_fmac_f32_e32 v150, v100, v193
	v_fmac_f32_e32 v151, v99, v193
	v_fmac_f32_e32 v152, v98, v193
	v_fmac_f32_e32 v153, v97, v193
	v_fmac_f32_e32 v154, v96, v193
	v_fmac_f32_e32 v155, v95, v193
	v_fmac_f32_e32 v156, v94, v193
	v_fmac_f32_e32 v157, v93, v193
	v_fmac_f32_e32 v158, v92, v193
	v_fmac_f32_e32 v159, v91, v193
	v_fmac_f32_e32 v160, v90, v193
	v_fmac_f32_e32 v161, v89, v193
	v_fmac_f32_e32 v162, v88, v193
	v_fmac_f32_e32 v163, v87, v193
	v_fmac_f32_e32 v164, v86, v193
	v_fmac_f32_e32 v165, v85, v193
	ds_read_b32 v193, v188 offset:56320
	s_waitcnt lgkmcnt(8)
	v_fmac_f32_e32 v151, v100, v194
	v_fmac_f32_e32 v152, v99, v194
	v_fmac_f32_e32 v153, v98, v194
	v_fmac_f32_e32 v154, v97, v194
	v_fmac_f32_e32 v155, v96, v194
	v_fmac_f32_e32 v156, v95, v194
	v_fmac_f32_e32 v157, v94, v194
	v_fmac_f32_e32 v158, v93, v194
	v_fmac_f32_e32 v159, v92, v194
	v_fmac_f32_e32 v160, v91, v194
	v_fmac_f32_e32 v161, v90, v194
	v_fmac_f32_e32 v162, v89, v194
	v_fmac_f32_e32 v163, v88, v194
	v_fmac_f32_e32 v164, v87, v194
	v_fmac_f32_e32 v165, v86, v194
	ds_read_b32 v194, v188 offset:57344
	s_waitcnt lgkmcnt(8)
	v_fmac_f32_e32 v152, v100, v195
	v_fmac_f32_e32 v153, v99, v195
	v_fmac_f32_e32 v154, v98, v195
	v_fmac_f32_e32 v155, v97, v195
	v_fmac_f32_e32 v156, v96, v195
	v_fmac_f32_e32 v157, v95, v195
	v_fmac_f32_e32 v158, v94, v195
	v_fmac_f32_e32 v159, v93, v195
	v_fmac_f32_e32 v160, v92, v195
	v_fmac_f32_e32 v161, v91, v195
	v_fmac_f32_e32 v162, v90, v195
	v_fmac_f32_e32 v163, v89, v195
	v_fmac_f32_e32 v164, v88, v195
	v_fmac_f32_e32 v165, v87, v195
	ds_read_b32 v195, v188 offset:58368
	s_waitcnt lgkmcnt(8)
	v_fmac_f32_e32 v153, v100, v196
	v_fmac_f32_e32 v154, v99, v196
	v_fmac_f32_e32 v155, v98, v196
	v_fmac_f32_e32 v156, v97, v196
	v_fmac_f32_e32 v157, v96, v196
	v_fmac_f32_e32 v158, v95, v196
	v_fmac_f32_e32 v159, v94, v196
	v_fmac_f32_e32 v160, v93, v196
	v_fmac_f32_e32 v161, v92, v196
	v_fmac_f32_e32 v162, v91, v196
	v_fmac_f32_e32 v163, v90, v196
	v_fmac_f32_e32 v164, v89, v196
	v_fmac_f32_e32 v165, v88, v196
	ds_read_b32 v196, v188 offset:59392
	s_waitcnt lgkmcnt(8)
	v_fmac_f32_e32 v154, v100, v197
	v_fmac_f32_e32 v155, v99, v197
	v_fmac_f32_e32 v156, v98, v197
	v_fmac_f32_e32 v157, v97, v197
	v_fmac_f32_e32 v158, v96, v197
	v_fmac_f32_e32 v159, v95, v197
	v_fmac_f32_e32 v160, v94, v197
	v_fmac_f32_e32 v161, v93, v197
	v_fmac_f32_e32 v162, v92, v197
	v_fmac_f32_e32 v163, v91, v197
	v_fmac_f32_e32 v164, v90, v197
	v_fmac_f32_e32 v165, v89, v197
	ds_read_b32 v197, v188 offset:60416
	s_waitcnt lgkmcnt(8)
	v_fmac_f32_e32 v155, v100, v198
	v_fmac_f32_e32 v156, v99, v198
	v_fmac_f32_e32 v157, v98, v198
	v_fmac_f32_e32 v158, v97, v198
	v_fmac_f32_e32 v159, v96, v198
	v_fmac_f32_e32 v160, v95, v198
	v_fmac_f32_e32 v161, v94, v198
	v_fmac_f32_e32 v162, v93, v198
	v_fmac_f32_e32 v163, v92, v198
	v_fmac_f32_e32 v164, v91, v198
	v_fmac_f32_e32 v165, v90, v198
	ds_read_b32 v198, v188 offset:61440
	s_waitcnt lgkmcnt(8)
; #define LAS __attribute__((address_space(3)))
; __device__ __forceinline__ void conv_loop(unsigned char* ws_, const float* const* in_, int l_, LAS unsigned char* lds, int tid, int bid, int G) {
;     ...
;             ConvStep<0>::run(acc, wv, U, rb, cch);
;             __syncthreads();
; #pragma unroll
;             for (int o = 0; o < 32; ++o) U[ring94(ring94(rb + o)) * 256 + cch] = acc[o];
;             __syncthreads();
; #pragma unroll
;             for (int i = 0; i < 8; ++i) { const int tok = 8 * w + i; f32x4 v = *(LAS f32x4*)(U + ring94(base + tok) * 256 + 4 * lane);
;                 const float mean = wave_sum((v[0] + v[1]) + (v[2] + v[3])) * (1.0f / 256.0f);
;                 v = v - mean; const float var = wave_sum((v[0] * v[0] + v[1] * v[1]) + (v[2] * v[2] + v[3] * v[3])) * (1.0f / 256.0f);
	v_fmac_f32_e32 v156, v100, v199
	v_fmac_f32_e32 v157, v99, v199
	v_fmac_f32_e32 v158, v98, v199
	v_fmac_f32_e32 v159, v97, v199
	v_fmac_f32_e32 v160, v96, v199
	v_fmac_f32_e32 v161, v95, v199
	v_fmac_f32_e32 v162, v94, v199
	v_fmac_f32_e32 v163, v93, v199
	v_fmac_f32_e32 v164, v92, v199
	v_fmac_f32_e32 v165, v91, v199
	ds_read_b32 v199, v188 offset:62464
	s_waitcnt lgkmcnt(8)
	v_fmac_f32_e32 v157, v100, v200
	v_fmac_f32_e32 v158, v99, v200
	v_fmac_f32_e32 v159, v98, v200
	v_fmac_f32_e32 v160, v97, v200
	v_fmac_f32_e32 v161, v96, v200
	v_fmac_f32_e32 v162, v95, v200
	v_fmac_f32_e32 v163, v94, v200
	v_fmac_f32_e32 v164, v93, v200
	v_fmac_f32_e32 v165, v92, v200
	s_waitcnt lgkmcnt(7)
	v_fmac_f32_e32 v158, v100, v192
	v_fmac_f32_e32 v159, v99, v192
	v_fmac_f32_e32 v160, v98, v192
	v_fmac_f32_e32 v161, v97, v192
	v_fmac_f32_e32 v162, v96, v192
	v_fmac_f32_e32 v163, v95, v192
	v_fmac_f32_e32 v164, v94, v192
	v_fmac_f32_e32 v165, v93, v192
	s_waitcnt lgkmcnt(6)
	v_fmac_f32_e32 v159, v100, v193
	v_fmac_f32_e32 v160, v99, v193
	v_fmac_f32_e32 v161, v98, v193
	v_fmac_f32_e32 v162, v97, v193
	v_fmac_f32_e32 v163, v96, v193
	v_fmac_f32_e32 v164, v95, v193
	v_fmac_f32_e32 v165, v94, v193
	s_waitcnt lgkmcnt(5)
	v_fmac_f32_e32 v160, v100, v194
	v_fmac_f32_e32 v161, v99, v194
	v_fmac_f32_e32 v162, v98, v194
	v_fmac_f32_e32 v163, v97, v194
	v_fmac_f32_e32 v164, v96, v194
	v_fmac_f32_e32 v165, v95, v194
	s_waitcnt lgkmcnt(4)
	v_fmac_f32_e32 v161, v100, v195
	v_fmac_f32_e32 v162, v99, v195
	v_fmac_f32_e32 v163, v98, v195
	v_fmac_f32_e32 v164, v97, v195
	v_fmac_f32_e32 v165, v96, v195
	s_waitcnt lgkmcnt(3)
	v_fmac_f32_e32 v162, v100, v196
	v_fmac_f32_e32 v163, v99, v196
	v_fmac_f32_e32 v164, v98, v196
	v_fmac_f32_e32 v165, v97, v196
	s_waitcnt lgkmcnt(2)
	v_fmac_f32_e32 v163, v100, v197
	v_fmac_f32_e32 v164, v99, v197
	v_fmac_f32_e32 v165, v98, v197
	s_waitcnt lgkmcnt(1)
	v_fmac_f32_e32 v164, v100, v198
	v_fmac_f32_e32 v165, v99, v198
	s_waitcnt lgkmcnt(0)
	v_fmac_f32_e32 v165, v100, v199
	ds_read_b32 v214, v230 offset:0
	ds_read_b32 v215, v230 offset:1024
	ds_read_b32 v216, v230 offset:2048
	ds_read_b32 v217, v230 offset:3072
	ds_read_b32 v218, v230 offset:4096
	ds_read_b32 v219, v230 offset:5120
	ds_read_b32 v220, v230 offset:6144
	ds_read_b32 v221, v230 offset:7168
	ds_read_b32 v222, v230 offset:8192
	ds_read_b32 v223, v230 offset:9216
	ds_read_b32 v224, v230 offset:10240
	ds_read_b32 v225, v230 offset:11264
	ds_read_b32 v226, v230 offset:12288
	ds_read_b32 v227, v230 offset:13312
	ds_read_b32 v228, v230 offset:14336
	s_barrier
	ds_write_b32 v188, v124 offset:0
	ds_write_b32 v188, v125 offset:1024
	ds_write_b32 v188, v126 offset:2048
	ds_write_b32 v188, v127 offset:3072
	ds_write_b32 v188, v128 offset:4096
	ds_write_b32 v188, v129 offset:5120
	ds_write_b32 v188, v130 offset:6144
	ds_write_b32 v188, v131 offset:7168
	ds_write_b32 v188, v132 offset:8192
	ds_write_b32 v188, v133 offset:9216
	ds_write_b32 v188, v134 offset:10240
	ds_write_b32 v188, v135 offset:11264
	ds_write_b32 v188, v136 offset:12288
	ds_write_b32 v188, v137 offset:13312
	ds_write_b32 v188, v148 offset:14336
	ds_write_b32 v188, v149 offset:15360
	ds_write_b32 v188, v150 offset:16384
	ds_write_b32 v188, v151 offset:17408
	ds_write_b32 v188, v152 offset:18432
	ds_write_b32 v188, v153 offset:19456
	ds_write_b32 v188, v154 offset:20480
	ds_write_b32 v188, v155 offset:21504
	ds_write_b32 v188, v156 offset:22528
	ds_write_b32 v188, v157 offset:23552
	ds_write_b32 v188, v158 offset:24576
	ds_write_b32 v188, v159 offset:25600
	ds_write_b32 v188, v160 offset:26624
	ds_write_b32 v188, v161 offset:27648
	ds_write_b32 v188, v162 offset:28672
	ds_write_b32 v188, v163 offset:29696
	ds_write_b32 v188, v164 offset:30720
	ds_write_b32 v188, v165 offset:31744
	v_add_u32_e32 v63, s26, v52
	v_cmp_lt_i32_e32 vcc, s91, v63
	v_lshlrev_b32_e32 v63, 10, v63
	v_add_u32_e32 v70, 0xfffe8800, v63
	v_cndmask_b32_e32 v63, v63, v70, vcc
	v_add_u32_e32 v63, v105, v63
	s_waitcnt lgkmcnt(0)
	s_barrier
	v_lshl_add_u32 v188, v52, 10, v105
	ds_read_b128 v[124:127], v188 offset:0
	ds_read_b128 v[128:131], v188 offset:1024
	ds_read_b128 v[132:135], v188 offset:2048
	ds_read_b128 v[148:151], v188 offset:3072
	ds_read_b128 v[152:155], v188 offset:4096
	ds_read_b128 v[156:159], v188 offset:5120
	ds_read_b128 v[160:163], v188 offset:6144
	ds_read_b128 v[164:167], v188 offset:7168
	s_mov_b32 s76, 0x1000
	s_mov_b32 s77, 0
	v_lshl_add_u64 v[206:207], v[48:49], 0, s[42:43]
	v_lshl_add_u64 v[48:49], v[48:49], 0, s[74:75]
	v_lshl_add_u64 v[44:45], v[44:45], 0, s[74:75]
	v_lshl_add_u64 v[42:43], v[42:43], 0, s[74:75]
	v_lshl_add_u64 v[208:209], v[206:207], 0, s[76:77]
	v_lshl_add_u64 v[210:211], v[208:209], 0, s[76:77]
	v_lshl_add_u64 v[212:213], v[210:211], 0, s[76:77]
	s_add_i32 s27, s27, -1
	s_waitcnt lgkmcnt(7)
	v_add_f32_e32 v168, v125, v124
	v_add_f32_e32 v194, v126, v127
	s_waitcnt lgkmcnt(6)
	v_add_f32_e32 v169, v129, v128
	v_add_f32_e32 v195, v130, v131
	s_waitcnt lgkmcnt(5)
	v_add_f32_e32 v170, v133, v132
	v_add_f32_e32 v196, v134, v135
	s_waitcnt lgkmcnt(4)
	v_add_f32_e32 v171, v149, v148
	v_add_f32_e32 v197, v150, v151
	s_waitcnt lgkmcnt(3)
	v_add_f32_e32 v172, v153, v152
	v_add_f32_e32 v198, v154, v155
	s_waitcnt lgkmcnt(2)
	v_add_f32_e32 v173, v157, v156
	v_add_f32_e32 v199, v158, v159
	s_waitcnt lgkmcnt(1)
	v_add_f32_e32 v192, v161, v160
	v_add_f32_e32 v200, v162, v163
	s_waitcnt lgkmcnt(0)
; #define LAS __attribute__((address_space(3)))
; __device__ __forceinline__ void conv_loop(unsigned char* ws_, const float* const* in_, int l_, LAS unsigned char* lds, int tid, int bid, int G) {
;     ...
;             for (int i = 0; i < 8; ++i) { const int tok = 8 * w + i; f32x4 v = *(LAS f32x4*)(U + ring94(base + tok) * 256 + 4 * lane);
;                 const float mean = wave_sum((v[0] + v[1]) + (v[2] + v[3])) * (1.0f / 256.0f);
;                 v = v - mean; const float var = wave_sum((v[0] * v[0] + v[1] * v[1]) + (v[2] * v[2] + v[3] * v[3])) * (1.0f / 256.0f);
	v_add_f32_e32 v193, v165, v164
	v_add_f32_e32 v201, v166, v167
	v_add_f32_e32 v168, v168, v194
	v_add_f32_e32 v169, v169, v195
	v_add_f32_e32 v170, v170, v196
	v_add_f32_e32 v171, v171, v197
	v_add_f32_e32 v172, v172, v198
	v_add_f32_e32 v173, v173, v199
	v_add_f32_e32 v192, v192, v200
	v_add_f32_e32 v193, v193, v201
	v_add_f32_dpp v168, v168, v168 quad_perm:[1,0,3,2] row_mask:0xf bank_mask:0xf
	v_add_f32_dpp v169, v169, v169 quad_perm:[1,0,3,2] row_mask:0xf bank_mask:0xf
	v_add_f32_dpp v170, v170, v170 quad_perm:[1,0,3,2] row_mask:0xf bank_mask:0xf
	v_add_f32_dpp v171, v171, v171 quad_perm:[1,0,3,2] row_mask:0xf bank_mask:0xf
	v_add_f32_dpp v172, v172, v172 quad_perm:[1,0,3,2] row_mask:0xf bank_mask:0xf
	v_add_f32_dpp v173, v173, v173 quad_perm:[1,0,3,2] row_mask:0xf bank_mask:0xf
	v_add_f32_dpp v192, v192, v192 quad_perm:[1,0,3,2] row_mask:0xf bank_mask:0xf
	v_add_f32_dpp v193, v193, v193 quad_perm:[1,0,3,2] row_mask:0xf bank_mask:0xf
	v_add_f32_dpp v168, v168, v168 quad_perm:[2,3,0,1] row_mask:0xf bank_mask:0xf
	v_add_f32_dpp v169, v169, v169 quad_perm:[2,3,0,1] row_mask:0xf bank_mask:0xf
	v_add_f32_dpp v170, v170, v170 quad_perm:[2,3,0,1] row_mask:0xf bank_mask:0xf
	v_add_f32_dpp v171, v171, v171 quad_perm:[2,3,0,1] row_mask:0xf bank_mask:0xf
	v_add_f32_dpp v172, v172, v172 quad_perm:[2,3,0,1] row_mask:0xf bank_mask:0xf
	v_add_f32_dpp v173, v173, v173 quad_perm:[2,3,0,1] row_mask:0xf bank_mask:0xf
	v_add_f32_dpp v192, v192, v192 quad_perm:[2,3,0,1] row_mask:0xf bank_mask:0xf
	v_add_f32_dpp v193, v193, v193 quad_perm:[2,3,0,1] row_mask:0xf bank_mask:0xf
	v_add_f32_dpp v168, v168, v168 row_half_mirror row_mask:0xf bank_mask:0xf
	v_add_f32_dpp v169, v169, v169 row_half_mirror row_mask:0xf bank_mask:0xf
	v_add_f32_dpp v170, v170, v170 row_half_mirror row_mask:0xf bank_mask:0xf
	v_add_f32_dpp v171, v171, v171 row_half_mirror row_mask:0xf bank_mask:0xf
	v_add_f32_dpp v172, v172, v172 row_half_mirror row_mask:0xf bank_mask:0xf
	v_add_f32_dpp v173, v173, v173 row_half_mirror row_mask:0xf bank_mask:0xf
	v_add_f32_dpp v192, v192, v192 row_half_mirror row_mask:0xf bank_mask:0xf
	v_add_f32_dpp v193, v193, v193 row_half_mirror row_mask:0xf bank_mask:0xf
	v_add_f32_dpp v168, v168, v168 row_mirror row_mask:0xf bank_mask:0xf
	v_add_f32_dpp v169, v169, v169 row_mirror row_mask:0xf bank_mask:0xf
	v_add_f32_dpp v170, v170, v170 row_mirror row_mask:0xf bank_mask:0xf
	v_add_f32_dpp v171, v171, v171 row_mirror row_mask:0xf bank_mask:0xf
	v_add_f32_dpp v172, v172, v172 row_mirror row_mask:0xf bank_mask:0xf
	v_add_f32_dpp v173, v173, v173 row_mirror row_mask:0xf bank_mask:0xf
	v_add_f32_dpp v192, v192, v192 row_mirror row_mask:0xf bank_mask:0xf
	v_add_f32_dpp v193, v193, v193 row_mirror row_mask:0xf bank_mask:0xf
	ds_bpermute_b32 v194, v110, v168
	ds_bpermute_b32 v195, v110, v169
	ds_bpermute_b32 v196, v110, v170
	ds_bpermute_b32 v197, v110, v171
	ds_bpermute_b32 v198, v110, v172
	ds_bpermute_b32 v199, v110, v173
	ds_bpermute_b32 v200, v110, v192
	ds_bpermute_b32 v201, v110, v193
	s_waitcnt lgkmcnt(7)
	v_add_f32_e32 v168, v168, v194
	s_waitcnt lgkmcnt(6)
	v_add_f32_e32 v169, v169, v195
	s_waitcnt lgkmcnt(5)
	v_add_f32_e32 v170, v170, v196
	s_waitcnt lgkmcnt(4)
	v_add_f32_e32 v171, v171, v197
	s_waitcnt lgkmcnt(3)
	v_add_f32_e32 v172, v172, v198
	s_waitcnt lgkmcnt(2)
	v_add_f32_e32 v173, v173, v199
	s_waitcnt lgkmcnt(1)
	v_add_f32_e32 v192, v192, v200
	s_waitcnt lgkmcnt(0)
	v_add_f32_e32 v193, v193, v201
	ds_bpermute_b32 v194, v111, v168
	ds_bpermute_b32 v195, v111, v169
	ds_bpermute_b32 v196, v111, v170
	ds_bpermute_b32 v197, v111, v171
	ds_bpermute_b32 v198, v111, v172
	ds_bpermute_b32 v199, v111, v173
	ds_bpermute_b32 v200, v111, v192
	ds_bpermute_b32 v201, v111, v193
	s_waitcnt lgkmcnt(7)
	v_add_f32_e32 v168, v168, v194
	s_waitcnt lgkmcnt(6)
	v_add_f32_e32 v169, v169, v195
	s_waitcnt lgkmcnt(5)
	v_add_f32_e32 v170, v170, v196
	s_waitcnt lgkmcnt(4)
	v_add_f32_e32 v171, v171, v197
	s_waitcnt lgkmcnt(3)
	v_add_f32_e32 v172, v172, v198
	s_waitcnt lgkmcnt(2)
	v_add_f32_e32 v173, v173, v199
	s_waitcnt lgkmcnt(1)
	v_add_f32_e32 v192, v192, v200
	s_waitcnt lgkmcnt(0)
	v_add_f32_e32 v193, v193, v201
	v_fmamk_f32 v124, v168, 0xbb800000, v124
	v_fmamk_f32 v125, v168, 0xbb800000, v125
	v_fmamk_f32 v126, v168, 0xbb800000, v126
	v_fmamk_f32 v127, v168, 0xbb800000, v127
	v_fmamk_f32 v128, v169, 0xbb800000, v128
	v_fmamk_f32 v129, v169, 0xbb800000, v129
	v_fmamk_f32 v130, v169, 0xbb800000, v130
	v_fmamk_f32 v131, v169, 0xbb800000, v131
	v_fmamk_f32 v132, v170, 0xbb800000, v132
	v_fmamk_f32 v133, v170, 0xbb800000, v133
	v_fmamk_f32 v134, v170, 0xbb800000, v134
	v_fmamk_f32 v135, v170, 0xbb800000, v135
	v_fmamk_f32 v148, v171, 0xbb800000, v148
	v_fmamk_f32 v149, v171, 0xbb800000, v149
	v_fmamk_f32 v150, v171, 0xbb800000, v150
	v_fmamk_f32 v151, v171, 0xbb800000, v151
	v_fmamk_f32 v152, v172, 0xbb800000, v152
	v_fmamk_f32 v153, v172, 0xbb800000, v153
	v_fmamk_f32 v154, v172, 0xbb800000, v154
	v_fmamk_f32 v155, v172, 0xbb800000, v155
	v_fmamk_f32 v156, v173, 0xbb800000, v156
	v_fmamk_f32 v157, v173, 0xbb800000, v157
	v_fmamk_f32 v158, v173, 0xbb800000, v158
	v_fmamk_f32 v159, v173, 0xbb800000, v159
	v_fmamk_f32 v160, v192, 0xbb800000, v160
	v_fmamk_f32 v161, v192, 0xbb800000, v161
	v_fmamk_f32 v162, v192, 0xbb800000, v162
	v_fmamk_f32 v163, v192, 0xbb800000, v163
	v_fmamk_f32 v164, v193, 0xbb800000, v164
	v_fmamk_f32 v165, v193, 0xbb800000, v165
	v_fmamk_f32 v166, v193, 0xbb800000, v166
	v_fmamk_f32 v167, v193, 0xbb800000, v167
	v_mul_f32_e32 v168, v125, v125
	v_mul_f32_e32 v194, v124, v124
	v_mul_f32_e32 v169, v129, v129
	v_mul_f32_e32 v195, v128, v128
; __device__ __forceinline__ void conv_loop(unsigned char* ws_, const float* const* in_, int l_, LAS unsigned char* lds, int tid, int bid, int G) {
;     ...
;                 v = v - mean; const float var = wave_sum((v[0] * v[0] + v[1] * v[1]) + (v[2] * v[2] + v[3] * v[3])) * (1.0f / 256.0f);
	v_mul_f32_e32 v170, v133, v133
	v_mul_f32_e32 v196, v132, v132
	v_mul_f32_e32 v171, v149, v149
	v_mul_f32_e32 v197, v148, v148
	v_mul_f32_e32 v172, v153, v153
	v_mul_f32_e32 v198, v152, v152
	v_mul_f32_e32 v173, v157, v157
	v_mul_f32_e32 v199, v156, v156
	v_mul_f32_e32 v192, v161, v161
	v_mul_f32_e32 v200, v160, v160
	v_mul_f32_e32 v193, v165, v165
	v_mul_f32_e32 v201, v164, v164
	v_add_f32_e32 v168, v168, v194
	v_add_f32_e32 v169, v169, v195
	v_add_f32_e32 v170, v170, v196
	v_add_f32_e32 v171, v171, v197
	v_add_f32_e32 v172, v172, v198
	v_add_f32_e32 v173, v173, v199
	v_add_f32_e32 v192, v192, v200
	v_add_f32_e32 v193, v193, v201
	v_mul_f32_e32 v194, v126, v126
	v_mul_f32_e32 v195, v130, v130
	v_mul_f32_e32 v196, v134, v134
	v_mul_f32_e32 v197, v150, v150
	v_mul_f32_e32 v198, v154, v154
	v_mul_f32_e32 v199, v158, v158
	v_mul_f32_e32 v200, v162, v162
	v_mul_f32_e32 v201, v166, v166
	v_mul_f32_e32 v202, v127, v127
	v_mul_f32_e32 v203, v131, v131
	v_mul_f32_e32 v204, v135, v135
	v_mul_f32_e32 v205, v151, v151
	v_add_f32_e32 v194, v194, v202
	v_add_f32_e32 v195, v195, v203
	v_add_f32_e32 v196, v196, v204
	v_add_f32_e32 v197, v197, v205
	v_mul_f32_e32 v202, v155, v155
	v_mul_f32_e32 v203, v159, v159
	v_mul_f32_e32 v204, v163, v163
	v_mul_f32_e32 v205, v167, v167
	v_add_f32_e32 v198, v198, v202
	v_add_f32_e32 v199, v199, v203
	v_add_f32_e32 v200, v200, v204
	v_add_f32_e32 v201, v201, v205
	v_add_f32_e32 v168, v168, v194
	v_add_f32_e32 v169, v169, v195
	v_add_f32_e32 v170, v170, v196
	v_add_f32_e32 v171, v171, v197
	v_add_f32_e32 v172, v172, v198
	v_add_f32_e32 v173, v173, v199
	v_add_f32_e32 v192, v192, v200
	v_add_f32_e32 v193, v193, v201
	v_add_f32_dpp v168, v168, v168 quad_perm:[1,0,3,2] row_mask:0xf bank_mask:0xf
	v_add_f32_dpp v169, v169, v169 quad_perm:[1,0,3,2] row_mask:0xf bank_mask:0xf
	v_add_f32_dpp v170, v170, v170 quad_perm:[1,0,3,2] row_mask:0xf bank_mask:0xf
	v_add_f32_dpp v171, v171, v171 quad_perm:[1,0,3,2] row_mask:0xf bank_mask:0xf
	v_add_f32_dpp v172, v172, v172 quad_perm:[1,0,3,2] row_mask:0xf bank_mask:0xf
	v_add_f32_dpp v173, v173, v173 quad_perm:[1,0,3,2] row_mask:0xf bank_mask:0xf
	v_add_f32_dpp v192, v192, v192 quad_perm:[1,0,3,2] row_mask:0xf bank_mask:0xf
	v_add_f32_dpp v193, v193, v193 quad_perm:[1,0,3,2] row_mask:0xf bank_mask:0xf
	v_add_f32_dpp v168, v168, v168 quad_perm:[2,3,0,1] row_mask:0xf bank_mask:0xf
	v_add_f32_dpp v169, v169, v169 quad_perm:[2,3,0,1] row_mask:0xf bank_mask:0xf
	v_add_f32_dpp v170, v170, v170 quad_perm:[2,3,0,1] row_mask:0xf bank_mask:0xf
	v_add_f32_dpp v171, v171, v171 quad_perm:[2,3,0,1] row_mask:0xf bank_mask:0xf
	v_add_f32_dpp v172, v172, v172 quad_perm:[2,3,0,1] row_mask:0xf bank_mask:0xf
	v_add_f32_dpp v173, v173, v173 quad_perm:[2,3,0,1] row_mask:0xf bank_mask:0xf
	v_add_f32_dpp v192, v192, v192 quad_perm:[2,3,0,1] row_mask:0xf bank_mask:0xf
	v_add_f32_dpp v193, v193, v193 quad_perm:[2,3,0,1] row_mask:0xf bank_mask:0xf
	v_add_f32_dpp v168, v168, v168 row_half_mirror row_mask:0xf bank_mask:0xf
	v_add_f32_dpp v169, v169, v169 row_half_mirror row_mask:0xf bank_mask:0xf
	v_add_f32_dpp v170, v170, v170 row_half_mirror row_mask:0xf bank_mask:0xf
	v_add_f32_dpp v171, v171, v171 row_half_mirror row_mask:0xf bank_mask:0xf
	v_add_f32_dpp v172, v172, v172 row_half_mirror row_mask:0xf bank_mask:0xf
	v_add_f32_dpp v173, v173, v173 row_half_mirror row_mask:0xf bank_mask:0xf
	v_add_f32_dpp v192, v192, v192 row_half_mirror row_mask:0xf bank_mask:0xf
	v_add_f32_dpp v193, v193, v193 row_half_mirror row_mask:0xf bank_mask:0xf
	v_add_f32_dpp v168, v168, v168 row_mirror row_mask:0xf bank_mask:0xf
	v_add_f32_dpp v169, v169, v169 row_mirror row_mask:0xf bank_mask:0xf
	v_add_f32_dpp v170, v170, v170 row_mirror row_mask:0xf bank_mask:0xf
	v_add_f32_dpp v171, v171, v171 row_mirror row_mask:0xf bank_mask:0xf
	v_add_f32_dpp v172, v172, v172 row_mirror row_mask:0xf bank_mask:0xf
	v_add_f32_dpp v173, v173, v173 row_mirror row_mask:0xf bank_mask:0xf
	v_add_f32_dpp v192, v192, v192 row_mirror row_mask:0xf bank_mask:0xf
	v_add_f32_dpp v193, v193, v193 row_mirror row_mask:0xf bank_mask:0xf
	ds_bpermute_b32 v194, v110, v168
	ds_bpermute_b32 v195, v110, v169
	ds_bpermute_b32 v196, v110, v170
	ds_bpermute_b32 v197, v110, v171
	ds_bpermute_b32 v198, v110, v172
	ds_bpermute_b32 v199, v110, v173
	ds_bpermute_b32 v200, v110, v192
	ds_bpermute_b32 v201, v110, v193
	s_waitcnt lgkmcnt(7)
	v_add_f32_e32 v168, v168, v194
	s_waitcnt lgkmcnt(6)
	v_add_f32_e32 v169, v169, v195
	s_waitcnt lgkmcnt(5)
	v_add_f32_e32 v170, v170, v196
	s_waitcnt lgkmcnt(4)
	v_add_f32_e32 v171, v171, v197
	s_waitcnt lgkmcnt(3)
	v_add_f32_e32 v172, v172, v198
	s_waitcnt lgkmcnt(2)
	v_add_f32_e32 v173, v173, v199
	s_waitcnt lgkmcnt(1)
	v_add_f32_e32 v192, v192, v200
	s_waitcnt lgkmcnt(0)
	v_add_f32_e32 v193, v193, v201
	ds_bpermute_b32 v194, v111, v168
	ds_bpermute_b32 v195, v111, v169
	ds_bpermute_b32 v196, v111, v170
	ds_bpermute_b32 v197, v111, v171
	ds_bpermute_b32 v198, v111, v172
	ds_bpermute_b32 v199, v111, v173
	ds_bpermute_b32 v200, v111, v192
	ds_bpermute_b32 v201, v111, v193
	s_waitcnt lgkmcnt(7)
	v_add_f32_e32 v168, v168, v194
	s_waitcnt lgkmcnt(6)
	v_add_f32_e32 v169, v169, v195
	s_waitcnt lgkmcnt(5)
	v_add_f32_e32 v170, v170, v196
	s_waitcnt lgkmcnt(4)
	v_add_f32_e32 v171, v171, v197
	s_waitcnt lgkmcnt(3)
	v_add_f32_e32 v172, v172, v198
	s_waitcnt lgkmcnt(2)
	v_add_f32_e32 v173, v173, v199
	s_waitcnt lgkmcnt(1)
	v_add_f32_e32 v192, v192, v200
	s_waitcnt lgkmcnt(0)
; __device__ __forceinline__ unsigned cvt_pk_bf16(float lo, float hi) { unsigned r; asm volatile("v_cvt_pk_bf16_f32 %0, %1, %2" : "=v"(r) : "v"(lo), "v"(hi)); return r; }
; __device__ __forceinline__ float sigmoidf_(float x) { return __builtin_amdgcn_rcpf(1.f + __expf(-x)); }
; __device__ __forceinline__ void conv_loop(unsigned char* ws_, const float* const* in_, int l_, LAS unsigned char* lds, int tid, int bid, int G) {
;     ...
;                 v = v - mean; const float var = wave_sum((v[0] * v[0] + v[1] * v[1]) + (v[2] * v[2] + v[3] * v[3])) * (1.0f / 256.0f);
;                 const float rstd = rsqrtf(var + LN_EPS); f32x4 y = v * rstd * gg + bb;
; #pragma unroll
;                 for (int e = 0; e < 4; ++e) y[e] = y[e] * sigmoidf_(y[e]);
;                 u32x2 wv2; wv2.x = cvt_pk_bf16(y[0], y[1]); wv2.y = cvt_pk_bf16(y[2], y[3]);
;                 *(u32x2*)(X.MIX + ((size_t)b * SEQ + t0 + tok) * DM + AW + 4 * lane) = wv2; }
	v_add_f32_e32 v193, v193, v201
	v_fmamk_f32 v168, v168, 0x3b800000, v176
	v_fmamk_f32 v169, v169, 0x3b800000, v176
	v_fmamk_f32 v170, v170, 0x3b800000, v176
	v_fmamk_f32 v171, v171, 0x3b800000, v176
	v_fmamk_f32 v172, v172, 0x3b800000, v176
	v_fmamk_f32 v173, v173, 0x3b800000, v176
	v_fmamk_f32 v192, v192, 0x3b800000, v176
	v_fmamk_f32 v193, v193, 0x3b800000, v176
	v_rsq_f32_e32 v168, v168
	v_rsq_f32_e32 v169, v169
	v_rsq_f32_e32 v170, v170
	v_rsq_f32_e32 v171, v171
	v_rsq_f32_e32 v172, v172
	v_rsq_f32_e32 v173, v173
	v_rsq_f32_e32 v192, v192
	v_rsq_f32_e32 v193, v193
	v_mul_f32_e32 v124, v124, v168
	v_mul_f32_e32 v125, v125, v168
	v_mul_f32_e32 v126, v126, v168
	v_mul_f32_e32 v127, v127, v168
	v_mul_f32_e32 v128, v128, v169
	v_mul_f32_e32 v129, v129, v169
	v_mul_f32_e32 v130, v130, v169
	v_mul_f32_e32 v131, v131, v169
	v_mul_f32_e32 v132, v132, v170
	v_mul_f32_e32 v133, v133, v170
	v_mul_f32_e32 v134, v134, v170
	v_mul_f32_e32 v135, v135, v170
	v_mul_f32_e32 v148, v148, v171
	v_mul_f32_e32 v149, v149, v171
	v_mul_f32_e32 v150, v150, v171
	v_mul_f32_e32 v151, v151, v171
	v_mul_f32_e32 v152, v152, v172
	v_mul_f32_e32 v153, v153, v172
	v_mul_f32_e32 v154, v154, v172
	v_mul_f32_e32 v155, v155, v172
	v_mul_f32_e32 v156, v156, v173
	v_mul_f32_e32 v157, v157, v173
	v_mul_f32_e32 v158, v158, v173
	v_mul_f32_e32 v159, v159, v173
	v_mul_f32_e32 v160, v160, v192
	v_mul_f32_e32 v161, v161, v192
	v_mul_f32_e32 v162, v162, v192
	v_mul_f32_e32 v163, v163, v192
	v_mul_f32_e32 v164, v164, v193
	v_mul_f32_e32 v165, v165, v193
	v_mul_f32_e32 v166, v166, v193
	v_mul_f32_e32 v167, v167, v193
	v_fma_f32 v124, v2, v124, v6
	v_fma_f32 v125, v3, v125, v7
	v_fma_f32 v126, v4, v126, v8
	v_fma_f32 v127, v5, v127, v9
	v_fma_f32 v128, v2, v128, v6
	v_fma_f32 v129, v3, v129, v7
	v_fma_f32 v130, v4, v130, v8
	v_fma_f32 v131, v5, v131, v9
	v_fma_f32 v132, v2, v132, v6
	v_fma_f32 v133, v3, v133, v7
	v_fma_f32 v134, v4, v134, v8
	v_fma_f32 v135, v5, v135, v9
	v_fma_f32 v148, v2, v148, v6
	v_fma_f32 v149, v3, v149, v7
	v_fma_f32 v150, v4, v150, v8
	v_fma_f32 v151, v5, v151, v9
	v_fma_f32 v152, v2, v152, v6
	v_fma_f32 v153, v3, v153, v7
	v_fma_f32 v154, v4, v154, v8
	v_fma_f32 v155, v5, v155, v9
	v_fma_f32 v156, v2, v156, v6
	v_fma_f32 v157, v3, v157, v7
	v_fma_f32 v158, v4, v158, v8
	v_fma_f32 v159, v5, v159, v9
	v_fma_f32 v160, v2, v160, v6
	v_fma_f32 v161, v3, v161, v7
	v_fma_f32 v162, v4, v162, v8
	v_fma_f32 v163, v5, v163, v9
	v_fma_f32 v164, v2, v164, v6
	v_fma_f32 v165, v3, v165, v7
	v_fma_f32 v166, v4, v166, v8
	v_fma_f32 v167, v5, v167, v9
	v_mul_f32_e32 v168, 0xbfb8aa3b, v124
	v_mul_f32_e32 v169, 0xbfb8aa3b, v125
	v_mul_f32_e32 v170, 0xbfb8aa3b, v126
	v_mul_f32_e32 v171, 0xbfb8aa3b, v127
	v_mul_f32_e32 v172, 0xbfb8aa3b, v128
	v_mul_f32_e32 v173, 0xbfb8aa3b, v129
	v_mul_f32_e32 v192, 0xbfb8aa3b, v130
	v_mul_f32_e32 v193, 0xbfb8aa3b, v131
	v_mul_f32_e32 v194, 0xbfb8aa3b, v132
	v_mul_f32_e32 v195, 0xbfb8aa3b, v133
	v_mul_f32_e32 v196, 0xbfb8aa3b, v134
	v_mul_f32_e32 v197, 0xbfb8aa3b, v135
	v_mul_f32_e32 v198, 0xbfb8aa3b, v148
	v_mul_f32_e32 v199, 0xbfb8aa3b, v149
	v_mul_f32_e32 v200, 0xbfb8aa3b, v150
	v_mul_f32_e32 v201, 0xbfb8aa3b, v151
	v_exp_f32_e32 v168, v168
	v_exp_f32_e32 v169, v169
	v_exp_f32_e32 v170, v170
	v_exp_f32_e32 v171, v171
	v_exp_f32_e32 v172, v172
	v_exp_f32_e32 v173, v173
	v_exp_f32_e32 v192, v192
	v_exp_f32_e32 v193, v193
	v_exp_f32_e32 v194, v194
	v_exp_f32_e32 v195, v195
	v_exp_f32_e32 v196, v196
	v_exp_f32_e32 v197, v197
	v_exp_f32_e32 v198, v198
	v_exp_f32_e32 v199, v199
	v_exp_f32_e32 v200, v200
	v_exp_f32_e32 v201, v201
	v_add_f32_e32 v168, 1.0, v168
	v_add_f32_e32 v169, 1.0, v169
	v_add_f32_e32 v170, 1.0, v170
	v_add_f32_e32 v171, 1.0, v171
	v_add_f32_e32 v172, 1.0, v172
	v_add_f32_e32 v173, 1.0, v173
	v_add_f32_e32 v192, 1.0, v192
	v_add_f32_e32 v193, 1.0, v193
	v_add_f32_e32 v194, 1.0, v194
	v_add_f32_e32 v195, 1.0, v195
	v_add_f32_e32 v196, 1.0, v196
	v_add_f32_e32 v197, 1.0, v197
	v_add_f32_e32 v198, 1.0, v198
	v_add_f32_e32 v199, 1.0, v199
	v_add_f32_e32 v200, 1.0, v200
	v_add_f32_e32 v201, 1.0, v201
	v_rcp_f32_e32 v168, v168
	v_rcp_f32_e32 v169, v169
	v_rcp_f32_e32 v170, v170
	v_rcp_f32_e32 v171, v171
	v_rcp_f32_e32 v172, v172
	v_rcp_f32_e32 v173, v173
	v_rcp_f32_e32 v192, v192
	v_rcp_f32_e32 v193, v193
	v_rcp_f32_e32 v194, v194
	v_rcp_f32_e32 v195, v195
	v_rcp_f32_e32 v196, v196
	v_rcp_f32_e32 v197, v197
	v_rcp_f32_e32 v198, v198
	v_rcp_f32_e32 v199, v199
	v_rcp_f32_e32 v200, v200
	v_rcp_f32_e32 v201, v201
	v_mul_f32_e32 v124, v124, v168
	v_mul_f32_e32 v125, v125, v169
; __device__ __forceinline__ unsigned cvt_pk_bf16(float lo, float hi) { unsigned r; asm volatile("v_cvt_pk_bf16_f32 %0, %1, %2" : "=v"(r) : "v"(lo), "v"(hi)); return r; }
; __device__ __forceinline__ float sigmoidf_(float x) { return __builtin_amdgcn_rcpf(1.f + __expf(-x)); }
; __device__ __forceinline__ void conv_loop(unsigned char* ws_, const float* const* in_, int l_, LAS unsigned char* lds, int tid, int bid, int G) {
;     ...
;                 const float rstd = rsqrtf(var + LN_EPS); f32x4 y = v * rstd * gg + bb;
; #pragma unroll
;                 for (int e = 0; e < 4; ++e) y[e] = y[e] * sigmoidf_(y[e]);
;                 u32x2 wv2; wv2.x = cvt_pk_bf16(y[0], y[1]); wv2.y = cvt_pk_bf16(y[2], y[3]);
;                 *(u32x2*)(X.MIX + ((size_t)b * SEQ + t0 + tok) * DM + AW + 4 * lane) = wv2; }
;             __syncthreads();
;             base = ring94(base + 64);
	v_mul_f32_e32 v126, v126, v170
	v_mul_f32_e32 v127, v127, v171
	v_mul_f32_e32 v128, v128, v172
	v_mul_f32_e32 v129, v129, v173
	v_mul_f32_e32 v130, v130, v192
	v_mul_f32_e32 v131, v131, v193
	v_mul_f32_e32 v132, v132, v194
	v_mul_f32_e32 v133, v133, v195
	v_mul_f32_e32 v134, v134, v196
	v_mul_f32_e32 v135, v135, v197
	v_mul_f32_e32 v148, v148, v198
	v_mul_f32_e32 v149, v149, v199
	v_mul_f32_e32 v150, v150, v200
	v_mul_f32_e32 v151, v151, v201
	v_cvt_pk_bf16_f32 v124, v124, v125
	v_cvt_pk_bf16_f32 v125, v126, v127
	v_cvt_pk_bf16_f32 v128, v128, v129
	v_cvt_pk_bf16_f32 v129, v130, v131
	v_cvt_pk_bf16_f32 v132, v132, v133
	v_cvt_pk_bf16_f32 v133, v134, v135
	v_cvt_pk_bf16_f32 v148, v148, v149
	v_cvt_pk_bf16_f32 v149, v150, v151
	global_store_dwordx2 v[206:207], v[124:125], off
	global_store_dwordx2 v[206:207], v[128:129], off offset:2048
	global_store_dwordx2 v[208:209], v[132:133], off
	global_store_dwordx2 v[208:209], v[148:149], off offset:2048
	v_mul_f32_e32 v168, 0xbfb8aa3b, v152
	v_mul_f32_e32 v169, 0xbfb8aa3b, v153
	v_mul_f32_e32 v170, 0xbfb8aa3b, v154
	v_mul_f32_e32 v171, 0xbfb8aa3b, v155
	v_mul_f32_e32 v172, 0xbfb8aa3b, v156
	v_mul_f32_e32 v173, 0xbfb8aa3b, v157
	v_mul_f32_e32 v192, 0xbfb8aa3b, v158
	v_mul_f32_e32 v193, 0xbfb8aa3b, v159
	v_mul_f32_e32 v194, 0xbfb8aa3b, v160
	v_mul_f32_e32 v195, 0xbfb8aa3b, v161
	v_mul_f32_e32 v196, 0xbfb8aa3b, v162
	v_mul_f32_e32 v197, 0xbfb8aa3b, v163
	v_mul_f32_e32 v198, 0xbfb8aa3b, v164
	v_mul_f32_e32 v199, 0xbfb8aa3b, v165
	v_mul_f32_e32 v200, 0xbfb8aa3b, v166
	v_mul_f32_e32 v201, 0xbfb8aa3b, v167
	v_exp_f32_e32 v168, v168
	v_exp_f32_e32 v169, v169
	v_exp_f32_e32 v170, v170
	v_exp_f32_e32 v171, v171
	v_exp_f32_e32 v172, v172
	v_exp_f32_e32 v173, v173
	v_exp_f32_e32 v192, v192
	v_exp_f32_e32 v193, v193
	v_exp_f32_e32 v194, v194
	v_exp_f32_e32 v195, v195
	v_exp_f32_e32 v196, v196
	v_exp_f32_e32 v197, v197
	v_exp_f32_e32 v198, v198
	v_exp_f32_e32 v199, v199
	v_exp_f32_e32 v200, v200
	v_exp_f32_e32 v201, v201
	v_add_f32_e32 v168, 1.0, v168
	v_add_f32_e32 v169, 1.0, v169
	v_add_f32_e32 v170, 1.0, v170
	v_add_f32_e32 v171, 1.0, v171
	v_add_f32_e32 v172, 1.0, v172
	v_add_f32_e32 v173, 1.0, v173
	v_add_f32_e32 v192, 1.0, v192
	v_add_f32_e32 v193, 1.0, v193
	v_add_f32_e32 v194, 1.0, v194
	v_add_f32_e32 v195, 1.0, v195
	v_add_f32_e32 v196, 1.0, v196
	v_add_f32_e32 v197, 1.0, v197
	v_add_f32_e32 v198, 1.0, v198
	v_add_f32_e32 v199, 1.0, v199
	v_add_f32_e32 v200, 1.0, v200
	v_add_f32_e32 v201, 1.0, v201
	v_rcp_f32_e32 v168, v168
	v_rcp_f32_e32 v169, v169
	v_rcp_f32_e32 v170, v170
	v_rcp_f32_e32 v171, v171
	v_rcp_f32_e32 v172, v172
	v_rcp_f32_e32 v173, v173
	v_rcp_f32_e32 v192, v192
	v_rcp_f32_e32 v193, v193
	v_rcp_f32_e32 v194, v194
	v_rcp_f32_e32 v195, v195
	v_rcp_f32_e32 v196, v196
	v_rcp_f32_e32 v197, v197
	v_rcp_f32_e32 v198, v198
	v_rcp_f32_e32 v199, v199
	v_rcp_f32_e32 v200, v200
	v_rcp_f32_e32 v201, v201
	v_mul_f32_e32 v152, v152, v168
	v_mul_f32_e32 v153, v153, v169
	v_mul_f32_e32 v154, v154, v170
	v_mul_f32_e32 v155, v155, v171
	v_mul_f32_e32 v156, v156, v172
	v_mul_f32_e32 v157, v157, v173
	v_mul_f32_e32 v158, v158, v192
	v_mul_f32_e32 v159, v159, v193
	v_mul_f32_e32 v160, v160, v194
	v_mul_f32_e32 v161, v161, v195
	v_mul_f32_e32 v162, v162, v196
	v_mul_f32_e32 v163, v163, v197
	v_mul_f32_e32 v164, v164, v198
	v_mul_f32_e32 v165, v165, v199
	v_mul_f32_e32 v166, v166, v200
	v_mul_f32_e32 v167, v167, v201
	v_cvt_pk_bf16_f32 v152, v152, v153
	v_cvt_pk_bf16_f32 v153, v154, v155
	v_cvt_pk_bf16_f32 v156, v156, v157
	v_cvt_pk_bf16_f32 v157, v158, v159
	v_cvt_pk_bf16_f32 v160, v160, v161
	v_cvt_pk_bf16_f32 v161, v162, v163
	v_cvt_pk_bf16_f32 v164, v164, v165
	v_cvt_pk_bf16_f32 v165, v166, v167
	global_store_dwordx2 v[210:211], v[152:153], off
	global_store_dwordx2 v[210:211], v[156:157], off offset:2048
	global_store_dwordx2 v[212:213], v[160:161], off
	global_store_dwordx2 v[212:213], v[164:165], off offset:2048
	s_cmp_eq_u32 s27, 0
	s_barrier
	s_cbranch_scc1 .LBB0_292
	ds_write_b32 v229, v214 offset:0
	ds_write_b32 v229, v215 offset:1024
	ds_write_b32 v229, v216 offset:2048
	ds_write_b32 v229, v217 offset:3072
	ds_write_b32 v229, v218 offset:4096
	ds_write_b32 v229, v219 offset:5120
	ds_write_b32 v229, v220 offset:6144
	ds_write_b32 v229, v221 offset:7168
	ds_write_b32 v229, v222 offset:8192
	ds_write_b32 v229, v223 offset:9216
	ds_write_b32 v229, v224 offset:10240
	ds_write_b32 v229, v225 offset:11264
	ds_write_b32 v229, v226 offset:12288
	ds_write_b32 v229, v227 offset:13312
	ds_write_b32 v229, v228 offset:14336

; #define LAS __attribute__((address_space(3)))
; __device__ __forceinline__ unsigned cvt_pk_bf16(float lo, float hi) { unsigned r; asm volatile("v_cvt_pk_bf16_f32 %0, %1, %2" : "=v"(r) : "v"(lo), "v"(hi)); return r; }
; __device__ __forceinline__ float rinv_from(u64 v) { return rsqrtf((float)v * (1.0f / 16777216.0f) * (1.0f / 1024.0f) + RMS_EPS); }
;     __device__ __forceinline__ void operator()(const f32x4 (&acc)[2][2][4][2], const Unit& u, int wr, int wc, int fr, int fq) const {
;         const int ln = fr + 16 * fq; const int colw = u.pn * BM + 64 * wc;
;         if (colw >= nvalid) return;
;         float rl[2];
; #pragma unroll
;         for (int ai = 0; ai < 2; ++ai) rl[ai] = rinv_from(ssq[u.pm * BM + ai * HALF + wr * 64 + ln]);
;         LAS unsigned char* sl = stg + (wr * 4 + wc) * EPI_STG_SLICE;
;         const int rr = ln >> 3, cc = ln & 7;
; #pragma unroll
;         for (int ai = 0; ai < 2; ++ai)
; #pragma unroll
;             for (int m = 0; m < 4; ++m) {
;                 const float sc = __shfl(rl[ai], 16 * m + fr);
; #pragma unroll
;                 for (int bj = 0; bj < 2; ++bj) {
;                     f32x4 v0 = acc[ai][bj][m][0] * sc, v1 = acc[ai][bj][m][1] * sc;
;                     if (ACT == 1) {
; #pragma unroll
;                         for (int e = 0; e < 4; ++e) { float a = fmaxf(v0[e], 0.f), b = fmaxf(v1[e], 0.f); v0[e] = a * a; v1[e] = b * b; }
;                     }
;                     u32x4 w; w.x = cvt_pk_bf16(v0[0], v0[1]); w.y = cvt_pk_bf16(v0[2], v0[3]); w.z = cvt_pk_bf16(v1[0], v1[1]); w.w = cvt_pk_bf16(v1[2], v1[3]);
;                     *(LAS u32x4*)(sl + fr * 144 + bj * 64 + fq * 16) = w;
;                 }
;                 const int rowb = u.pm * BM + ai * HALF + wr * 64 + m * 16;
; #pragma unroll
;                 for (int i = 0; i < 2; ++i) { const int r = rr + 8 * i; const u32x4 q = *(const LAS u32x4*)(sl + r * 144 + cc * 16);
;                     __builtin_nontemporal_store(q, (u32x4*)(O + (size_t)(rowb + r) * ldc + colw + cc * 8)); }
.LBB0_519:
	s_lshl_b32 s2, s2, 8
	s_add_i32 s2, s2, s79
	v_or_b32_e32 v162, s2, v155
	v_ashrrev_i32_e32 v163, 31, v162
	v_lshl_add_u64 v[162:163], v[162:163], 3, s[28:29]
	global_load_dwordx2 v[164:165], v[162:163], off
	s_nop 0
	global_load_dwordx2 v[162:163], v[162:163], off offset:1024
	s_mov_b32 s4, 0x33800000
	s_ashr_i32 s27, s26, 31
	s_or_b32 s3, s2, 16
	s_waitcnt vmcnt(0)
	v_ffbh_u32_e32 v153, v165
	v_min_u32_e32 v153, 32, v153
	v_lshlrev_b64 v[164:165], v153, v[164:165]
	v_min_u32_e32 v161, 1, v164
	v_or_b32_e32 v161, v165, v161
	v_cvt_f32_u32_e32 v161, v161
	v_sub_u32_e32 v153, 32, v153
	v_ldexp_f32 v165, v161, v153
	v_ffbh_u32_e32 v153, v163
	v_min_u32_e32 v153, 32, v153
	v_lshlrev_b64 v[162:163], v153, v[162:163]
	v_min_u32_e32 v161, 1, v162
	v_or_b32_e32 v161, v163, v161
	v_cvt_f32_u32_e32 v161, v161
	v_sub_u32_e32 v153, 32, v153
	v_ldexp_f32 v164, v161, v153
	v_pk_mul_f32 v[162:163], v[164:165], s[4:5] op_sel_hi:[1,0]
	s_mov_b32 s4, 0x3a800000
	v_pk_fma_f32 v[162:163], v[162:163], s[4:5], v[138:139] op_sel_hi:[1,0,0]
	s_nop 0
	v_mul_f32_e32 v153, 0x4b800000, v163
	v_cmp_gt_f32_e64 s[40:41], s70, v163
	v_cmp_gt_f32_e32 vcc, s70, v162
	s_nop 0
	v_cndmask_b32_e64 v153, v163, v153, s[40:41]
	v_rsq_f32_e32 v153, v153
	s_nop 0
	v_mul_f32_e32 v161, 0x45800000, v153
	v_cndmask_b32_e64 v163, v153, v161, s[40:41]
	v_mul_f32_e32 v153, 0x4b800000, v162
	v_cndmask_b32_e32 v153, v162, v153, vcc
	v_rsq_f32_e32 v153, v153
	s_lshl_b64 s[40:41], s[26:27], 1
	v_mul_f32_e32 v161, 0x45800000, v153
	v_cndmask_b32_e32 v161, v153, v161, vcc
	v_and_or_b32 v153, v177, 64, v1
	v_lshlrev_b32_e32 v162, 2, v153
	ds_bpermute_b32 v192, v162, v163
	ds_bpermute_b32 v194, v162, v163 offset:64
	ds_bpermute_b32 v196, v162, v163 offset:128
	ds_bpermute_b32 v198, v162, v163 offset:192
	ds_bpermute_b32 v200, v162, v161
	ds_bpermute_b32 v202, v162, v161 offset:64
	ds_bpermute_b32 v204, v162, v161 offset:128
	ds_bpermute_b32 v206, v162, v161 offset:192
	v_and_b32_e32 v210, 1, v177
	v_and_b32_e32 v211, 14, v177
	v_cmp_eq_u32_e64 s[92:93], 0, v210
	v_lshlrev_b32_e32 v208, 13, v211
	s_lshl_b32 s7, s2, 13
	v_lshl_add_u32 v208, v210, 6, v208
	v_bfe_u32 v211, v177, 4, 2
	v_lshl_add_u32 v208, v211, 4, v208
	v_add_u32_e32 v209, 0x2000, v208
	s_add_u32 s62, s44, s7
	s_addc_u32 s63, s45, 0
	s_lshl_b32 s7, s26, 1
	s_add_u32 s62, s62, s7
	s_addc_u32 s63, s63, 0
	s_waitcnt lgkmcnt(7)
	s_mov_b32 s64, s62
	s_mov_b32 s65, s63
	v_pk_mul_f32 v[126:127], v[126:127], v[192:193] op_sel_hi:[1,0]
	v_pk_mul_f32 v[128:129], v[128:129], v[192:193] op_sel_hi:[1,0]
	v_pk_mul_f32 v[122:123], v[122:123], v[192:193] op_sel_hi:[1,0]
	v_pk_mul_f32 v[124:125], v[124:125], v[192:193] op_sel_hi:[1,0]
	v_max_f32_e32 v126, 0, v126
	v_max_f32_e32 v127, 0, v127
	v_max_f32_e32 v128, 0, v128
	v_max_f32_e32 v129, 0, v129
	v_max_f32_e32 v122, 0, v122
	v_max_f32_e32 v123, 0, v123
	v_max_f32_e32 v124, 0, v124
	v_max_f32_e32 v125, 0, v125
	v_pk_mul_f32 v[126:127], v[126:127], v[126:127]
	v_pk_mul_f32 v[128:129], v[128:129], v[128:129]
	v_pk_mul_f32 v[122:123], v[122:123], v[122:123]
	v_pk_mul_f32 v[124:125], v[124:125], v[124:125]
	v_cvt_pk_bf16_f32 v126, v126, v127
	v_cvt_pk_bf16_f32 v127, v128, v129
	v_cvt_pk_bf16_f32 v128, v122, v123
	v_cvt_pk_bf16_f32 v129, v124, v125
	v_pk_mul_f32 v[118:119], v[118:119], v[192:193] op_sel_hi:[1,0]
	v_pk_mul_f32 v[120:121], v[120:121], v[192:193] op_sel_hi:[1,0]
	v_pk_mul_f32 v[114:115], v[114:115], v[192:193] op_sel_hi:[1,0]
	v_pk_mul_f32 v[116:117], v[116:117], v[192:193] op_sel_hi:[1,0]
	v_max_f32_e32 v118, 0, v118
	v_max_f32_e32 v119, 0, v119
	v_max_f32_e32 v120, 0, v120
	v_max_f32_e32 v121, 0, v121
	v_max_f32_e32 v114, 0, v114
	v_max_f32_e32 v115, 0, v115
	v_max_f32_e32 v116, 0, v116
	v_max_f32_e32 v117, 0, v117
	v_pk_mul_f32 v[118:119], v[118:119], v[118:119]
	v_pk_mul_f32 v[120:121], v[120:121], v[120:121]
	v_pk_mul_f32 v[114:115], v[114:115], v[114:115]
	v_pk_mul_f32 v[116:117], v[116:117], v[116:117]
	v_cvt_pk_bf16_f32 v118, v118, v119
	v_cvt_pk_bf16_f32 v119, v120, v121
	v_cvt_pk_bf16_f32 v120, v114, v115
	v_cvt_pk_bf16_f32 v121, v116, v117
	v_cndmask_b32_e64 v122, v126, v118, s[92:93]
	v_cndmask_b32_e64 v123, v127, v119, s[92:93]
	v_cndmask_b32_e64 v124, v128, v120, s[92:93]
	v_cndmask_b32_e64 v125, v129, v121, s[92:93]
	v_mov_b32_dpp v114, v122 quad_perm:[1,0,3,2] row_mask:0xf bank_mask:0xf
	v_mov_b32_dpp v115, v123 quad_perm:[1,0,3,2] row_mask:0xf bank_mask:0xf
	v_mov_b32_dpp v116, v124 quad_perm:[1,0,3,2] row_mask:0xf bank_mask:0xf
	v_mov_b32_dpp v117, v125 quad_perm:[1,0,3,2] row_mask:0xf bank_mask:0xf
	v_cndmask_b32_e64 v126, v114, v126, s[92:93]
	v_cndmask_b32_e64 v127, v115, v127, s[92:93]
	v_cndmask_b32_e64 v128, v116, v128, s[92:93]
	v_cndmask_b32_e64 v129, v117, v129, s[92:93]
	v_cndmask_b32_e64 v118, v118, v114, s[92:93]
	v_cndmask_b32_e64 v119, v119, v115, s[92:93]
	v_cndmask_b32_e64 v120, v120, v116, s[92:93]
	v_cndmask_b32_e64 v121, v121, v117, s[92:93]
	global_store_dwordx4 v208, v[126:129], s[64:65] nt
	global_store_dwordx4 v209, v[118:121], s[64:65] nt
	s_waitcnt lgkmcnt(6)
; #define LAS __attribute__((address_space(3)))
; __device__ __forceinline__ unsigned cvt_pk_bf16(float lo, float hi) { unsigned r; asm volatile("v_cvt_pk_bf16_f32 %0, %1, %2" : "=v"(r) : "v"(lo), "v"(hi)); return r; }
;     __device__ __forceinline__ void operator()(const f32x4 (&acc)[2][2][4][2], const Unit& u, int wr, int wc, int fr, int fq) const {
;     ...
;         for (int ai = 0; ai < 2; ++ai)
; #pragma unroll
;             for (int m = 0; m < 4; ++m) {
;                 const float sc = __shfl(rl[ai], 16 * m + fr);
; #pragma unroll
;                 for (int bj = 0; bj < 2; ++bj) {
;                     f32x4 v0 = acc[ai][bj][m][0] * sc, v1 = acc[ai][bj][m][1] * sc;
;                     if (ACT == 1) {
; #pragma unroll
;                         for (int e = 0; e < 4; ++e) { float a = fmaxf(v0[e], 0.f), b = fmaxf(v1[e], 0.f); v0[e] = a * a; v1[e] = b * b; }
;                     }
;                     u32x4 w; w.x = cvt_pk_bf16(v0[0], v0[1]); w.y = cvt_pk_bf16(v0[2], v0[3]); w.z = cvt_pk_bf16(v1[0], v1[1]); w.w = cvt_pk_bf16(v1[2], v1[3]);
;                     *(LAS u32x4*)(sl + fr * 144 + bj * 64 + fq * 16) = w;
;                 }
;                 const int rowb = u.pm * BM + ai * HALF + wr * 64 + m * 16;
; #pragma unroll
;                 for (int i = 0; i < 2; ++i) { const int r = rr + 8 * i; const u32x4 q = *(const LAS u32x4*)(sl + r * 144 + cc * 16);
;                     __builtin_nontemporal_store(q, (u32x4*)(O + (size_t)(rowb + r) * ldc + colw + cc * 8)); }
	s_add_u32 s64, s62, 0x20000
	s_addc_u32 s65, s63, 0
	v_pk_mul_f32 v[110:111], v[110:111], v[194:195] op_sel_hi:[1,0]
	v_pk_mul_f32 v[112:113], v[112:113], v[194:195] op_sel_hi:[1,0]
	v_pk_mul_f32 v[106:107], v[106:107], v[194:195] op_sel_hi:[1,0]
	v_pk_mul_f32 v[108:109], v[108:109], v[194:195] op_sel_hi:[1,0]
	v_max_f32_e32 v110, 0, v110
	v_max_f32_e32 v111, 0, v111
	v_max_f32_e32 v112, 0, v112
	v_max_f32_e32 v113, 0, v113
	v_max_f32_e32 v106, 0, v106
	v_max_f32_e32 v107, 0, v107
	v_max_f32_e32 v108, 0, v108
	v_max_f32_e32 v109, 0, v109
	v_pk_mul_f32 v[110:111], v[110:111], v[110:111]
	v_pk_mul_f32 v[112:113], v[112:113], v[112:113]
	v_pk_mul_f32 v[106:107], v[106:107], v[106:107]
	v_pk_mul_f32 v[108:109], v[108:109], v[108:109]
	v_cvt_pk_bf16_f32 v110, v110, v111
	v_cvt_pk_bf16_f32 v111, v112, v113
	v_cvt_pk_bf16_f32 v112, v106, v107
	v_cvt_pk_bf16_f32 v113, v108, v109
	v_pk_mul_f32 v[102:103], v[102:103], v[194:195] op_sel_hi:[1,0]
	v_pk_mul_f32 v[104:105], v[104:105], v[194:195] op_sel_hi:[1,0]
	v_pk_mul_f32 v[98:99], v[98:99], v[194:195] op_sel_hi:[1,0]
	v_pk_mul_f32 v[100:101], v[100:101], v[194:195] op_sel_hi:[1,0]
	v_max_f32_e32 v102, 0, v102
	v_max_f32_e32 v103, 0, v103
	v_max_f32_e32 v104, 0, v104
	v_max_f32_e32 v105, 0, v105
	v_max_f32_e32 v98, 0, v98
	v_max_f32_e32 v99, 0, v99
	v_max_f32_e32 v100, 0, v100
	v_max_f32_e32 v101, 0, v101
	v_pk_mul_f32 v[102:103], v[102:103], v[102:103]
	v_pk_mul_f32 v[104:105], v[104:105], v[104:105]
	v_pk_mul_f32 v[98:99], v[98:99], v[98:99]
	v_pk_mul_f32 v[100:101], v[100:101], v[100:101]
	v_cvt_pk_bf16_f32 v102, v102, v103
	v_cvt_pk_bf16_f32 v103, v104, v105
	v_cvt_pk_bf16_f32 v104, v98, v99
	v_cvt_pk_bf16_f32 v105, v100, v101
	v_cndmask_b32_e64 v106, v110, v102, s[92:93]
	v_cndmask_b32_e64 v107, v111, v103, s[92:93]
	v_cndmask_b32_e64 v108, v112, v104, s[92:93]
	v_cndmask_b32_e64 v109, v113, v105, s[92:93]
	v_mov_b32_dpp v98, v106 quad_perm:[1,0,3,2] row_mask:0xf bank_mask:0xf
	v_mov_b32_dpp v99, v107 quad_perm:[1,0,3,2] row_mask:0xf bank_mask:0xf
	v_mov_b32_dpp v100, v108 quad_perm:[1,0,3,2] row_mask:0xf bank_mask:0xf
	v_mov_b32_dpp v101, v109 quad_perm:[1,0,3,2] row_mask:0xf bank_mask:0xf
	v_cndmask_b32_e64 v110, v98, v110, s[92:93]
	v_cndmask_b32_e64 v111, v99, v111, s[92:93]
	v_cndmask_b32_e64 v112, v100, v112, s[92:93]
	v_cndmask_b32_e64 v113, v101, v113, s[92:93]
	v_cndmask_b32_e64 v102, v102, v98, s[92:93]
	v_cndmask_b32_e64 v103, v103, v99, s[92:93]
	v_cndmask_b32_e64 v104, v104, v100, s[92:93]
	v_cndmask_b32_e64 v105, v105, v101, s[92:93]
	global_store_dwordx4 v208, v[110:113], s[64:65] nt
	global_store_dwordx4 v209, v[102:105], s[64:65] nt
	s_waitcnt lgkmcnt(5)
	s_add_u32 s64, s62, 0x40000
	s_addc_u32 s65, s63, 0
	v_pk_mul_f32 v[94:95], v[94:95], v[196:197] op_sel_hi:[1,0]
	v_pk_mul_f32 v[96:97], v[96:97], v[196:197] op_sel_hi:[1,0]
	v_pk_mul_f32 v[90:91], v[90:91], v[196:197] op_sel_hi:[1,0]
	v_pk_mul_f32 v[92:93], v[92:93], v[196:197] op_sel_hi:[1,0]
	v_max_f32_e32 v94, 0, v94
	v_max_f32_e32 v95, 0, v95
	v_max_f32_e32 v96, 0, v96
	v_max_f32_e32 v97, 0, v97
	v_max_f32_e32 v90, 0, v90
	v_max_f32_e32 v91, 0, v91
	v_max_f32_e32 v92, 0, v92
	v_max_f32_e32 v93, 0, v93
	v_pk_mul_f32 v[94:95], v[94:95], v[94:95]
	v_pk_mul_f32 v[96:97], v[96:97], v[96:97]
	v_pk_mul_f32 v[90:91], v[90:91], v[90:91]
	v_pk_mul_f32 v[92:93], v[92:93], v[92:93]
	v_cvt_pk_bf16_f32 v94, v94, v95
	v_cvt_pk_bf16_f32 v95, v96, v97
	v_cvt_pk_bf16_f32 v96, v90, v91
	v_cvt_pk_bf16_f32 v97, v92, v93
	v_pk_mul_f32 v[86:87], v[86:87], v[196:197] op_sel_hi:[1,0]
	v_pk_mul_f32 v[88:89], v[88:89], v[196:197] op_sel_hi:[1,0]
	v_pk_mul_f32 v[82:83], v[82:83], v[196:197] op_sel_hi:[1,0]
	v_pk_mul_f32 v[84:85], v[84:85], v[196:197] op_sel_hi:[1,0]
	v_max_f32_e32 v86, 0, v86
	v_max_f32_e32 v87, 0, v87
	v_max_f32_e32 v88, 0, v88
	v_max_f32_e32 v89, 0, v89
	v_max_f32_e32 v82, 0, v82
	v_max_f32_e32 v83, 0, v83
	v_max_f32_e32 v84, 0, v84
	v_max_f32_e32 v85, 0, v85
	v_pk_mul_f32 v[86:87], v[86:87], v[86:87]
	v_pk_mul_f32 v[88:89], v[88:89], v[88:89]
	v_pk_mul_f32 v[82:83], v[82:83], v[82:83]
	v_pk_mul_f32 v[84:85], v[84:85], v[84:85]
	v_cvt_pk_bf16_f32 v86, v86, v87
	v_cvt_pk_bf16_f32 v87, v88, v89
	v_cvt_pk_bf16_f32 v88, v82, v83
	v_cvt_pk_bf16_f32 v89, v84, v85
	v_cndmask_b32_e64 v90, v94, v86, s[92:93]
	v_cndmask_b32_e64 v91, v95, v87, s[92:93]
	v_cndmask_b32_e64 v92, v96, v88, s[92:93]
	v_cndmask_b32_e64 v93, v97, v89, s[92:93]
	v_mov_b32_dpp v82, v90 quad_perm:[1,0,3,2] row_mask:0xf bank_mask:0xf
	v_mov_b32_dpp v83, v91 quad_perm:[1,0,3,2] row_mask:0xf bank_mask:0xf
	v_mov_b32_dpp v84, v92 quad_perm:[1,0,3,2] row_mask:0xf bank_mask:0xf
	v_mov_b32_dpp v85, v93 quad_perm:[1,0,3,2] row_mask:0xf bank_mask:0xf
	v_cndmask_b32_e64 v94, v82, v94, s[92:93]
	v_cndmask_b32_e64 v95, v83, v95, s[92:93]
	v_cndmask_b32_e64 v96, v84, v96, s[92:93]
	v_cndmask_b32_e64 v97, v85, v97, s[92:93]
	v_cndmask_b32_e64 v86, v86, v82, s[92:93]
	v_cndmask_b32_e64 v87, v87, v83, s[92:93]
	v_cndmask_b32_e64 v88, v88, v84, s[92:93]
	v_cndmask_b32_e64 v89, v89, v85, s[92:93]
	global_store_dwordx4 v208, v[94:97], s[64:65] nt
	global_store_dwordx4 v209, v[86:89], s[64:65] nt
	s_waitcnt lgkmcnt(4)
; #define LAS __attribute__((address_space(3)))
; __device__ __forceinline__ unsigned cvt_pk_bf16(float lo, float hi) { unsigned r; asm volatile("v_cvt_pk_bf16_f32 %0, %1, %2" : "=v"(r) : "v"(lo), "v"(hi)); return r; }
;     __device__ __forceinline__ void operator()(const f32x4 (&acc)[2][2][4][2], const Unit& u, int wr, int wc, int fr, int fq) const {
;     ...
;         for (int ai = 0; ai < 2; ++ai)
; #pragma unroll
;             for (int m = 0; m < 4; ++m) {
;                 const float sc = __shfl(rl[ai], 16 * m + fr);
; #pragma unroll
;                 for (int bj = 0; bj < 2; ++bj) {
;                     f32x4 v0 = acc[ai][bj][m][0] * sc, v1 = acc[ai][bj][m][1] * sc;
;                     if (ACT == 1) {
; #pragma unroll
;                         for (int e = 0; e < 4; ++e) { float a = fmaxf(v0[e], 0.f), b = fmaxf(v1[e], 0.f); v0[e] = a * a; v1[e] = b * b; }
;                     }
;                     u32x4 w; w.x = cvt_pk_bf16(v0[0], v0[1]); w.y = cvt_pk_bf16(v0[2], v0[3]); w.z = cvt_pk_bf16(v1[0], v1[1]); w.w = cvt_pk_bf16(v1[2], v1[3]);
;                     *(LAS u32x4*)(sl + fr * 144 + bj * 64 + fq * 16) = w;
;                 }
;                 const int rowb = u.pm * BM + ai * HALF + wr * 64 + m * 16;
; #pragma unroll
;                 for (int i = 0; i < 2; ++i) { const int r = rr + 8 * i; const u32x4 q = *(const LAS u32x4*)(sl + r * 144 + cc * 16);
;                     __builtin_nontemporal_store(q, (u32x4*)(O + (size_t)(rowb + r) * ldc + colw + cc * 8)); }
	s_add_u32 s64, s62, 0x60000
	s_addc_u32 s65, s63, 0
	v_pk_mul_f32 v[78:79], v[78:79], v[198:199] op_sel_hi:[1,0]
	v_pk_mul_f32 v[80:81], v[80:81], v[198:199] op_sel_hi:[1,0]
	v_pk_mul_f32 v[74:75], v[74:75], v[198:199] op_sel_hi:[1,0]
	v_pk_mul_f32 v[76:77], v[76:77], v[198:199] op_sel_hi:[1,0]
	v_max_f32_e32 v78, 0, v78
	v_max_f32_e32 v79, 0, v79
	v_max_f32_e32 v80, 0, v80
	v_max_f32_e32 v81, 0, v81
	v_max_f32_e32 v74, 0, v74
	v_max_f32_e32 v75, 0, v75
	v_max_f32_e32 v76, 0, v76
	v_max_f32_e32 v77, 0, v77
	v_pk_mul_f32 v[78:79], v[78:79], v[78:79]
	v_pk_mul_f32 v[80:81], v[80:81], v[80:81]
	v_pk_mul_f32 v[74:75], v[74:75], v[74:75]
	v_pk_mul_f32 v[76:77], v[76:77], v[76:77]
	v_cvt_pk_bf16_f32 v78, v78, v79
	v_cvt_pk_bf16_f32 v79, v80, v81
	v_cvt_pk_bf16_f32 v80, v74, v75
	v_cvt_pk_bf16_f32 v81, v76, v77
	v_pk_mul_f32 v[70:71], v[70:71], v[198:199] op_sel_hi:[1,0]
	v_pk_mul_f32 v[72:73], v[72:73], v[198:199] op_sel_hi:[1,0]
	v_pk_mul_f32 v[66:67], v[66:67], v[198:199] op_sel_hi:[1,0]
	v_pk_mul_f32 v[68:69], v[68:69], v[198:199] op_sel_hi:[1,0]
	v_max_f32_e32 v70, 0, v70
	v_max_f32_e32 v71, 0, v71
	v_max_f32_e32 v72, 0, v72
	v_max_f32_e32 v73, 0, v73
	v_max_f32_e32 v66, 0, v66
	v_max_f32_e32 v67, 0, v67
	v_max_f32_e32 v68, 0, v68
	v_max_f32_e32 v69, 0, v69
	v_pk_mul_f32 v[70:71], v[70:71], v[70:71]
	v_pk_mul_f32 v[72:73], v[72:73], v[72:73]
	v_pk_mul_f32 v[66:67], v[66:67], v[66:67]
	v_pk_mul_f32 v[68:69], v[68:69], v[68:69]
	v_cvt_pk_bf16_f32 v70, v70, v71
	v_cvt_pk_bf16_f32 v71, v72, v73
	v_cvt_pk_bf16_f32 v72, v66, v67
	v_cvt_pk_bf16_f32 v73, v68, v69
	v_cndmask_b32_e64 v74, v78, v70, s[92:93]
	v_cndmask_b32_e64 v75, v79, v71, s[92:93]
	v_cndmask_b32_e64 v76, v80, v72, s[92:93]
	v_cndmask_b32_e64 v77, v81, v73, s[92:93]
	v_mov_b32_dpp v66, v74 quad_perm:[1,0,3,2] row_mask:0xf bank_mask:0xf
	v_mov_b32_dpp v67, v75 quad_perm:[1,0,3,2] row_mask:0xf bank_mask:0xf
	v_mov_b32_dpp v68, v76 quad_perm:[1,0,3,2] row_mask:0xf bank_mask:0xf
	v_mov_b32_dpp v69, v77 quad_perm:[1,0,3,2] row_mask:0xf bank_mask:0xf
	v_cndmask_b32_e64 v78, v66, v78, s[92:93]
	v_cndmask_b32_e64 v79, v67, v79, s[92:93]
	v_cndmask_b32_e64 v80, v68, v80, s[92:93]
	v_cndmask_b32_e64 v81, v69, v81, s[92:93]
	v_cndmask_b32_e64 v70, v70, v66, s[92:93]
	v_cndmask_b32_e64 v71, v71, v67, s[92:93]
	v_cndmask_b32_e64 v72, v72, v68, s[92:93]
	v_cndmask_b32_e64 v73, v73, v69, s[92:93]
	global_store_dwordx4 v208, v[78:81], s[64:65] nt
	global_store_dwordx4 v209, v[70:73], s[64:65] nt
	s_waitcnt lgkmcnt(3)
	s_add_u32 s64, s62, 0x100000
	s_addc_u32 s65, s63, 0
	v_pk_mul_f32 v[62:63], v[62:63], v[200:201] op_sel_hi:[1,0]
	v_pk_mul_f32 v[64:65], v[64:65], v[200:201] op_sel_hi:[1,0]
	v_pk_mul_f32 v[58:59], v[58:59], v[200:201] op_sel_hi:[1,0]
	v_pk_mul_f32 v[60:61], v[60:61], v[200:201] op_sel_hi:[1,0]
	v_max_f32_e32 v62, 0, v62
	v_max_f32_e32 v63, 0, v63
	v_max_f32_e32 v64, 0, v64
	v_max_f32_e32 v65, 0, v65
	v_max_f32_e32 v58, 0, v58
	v_max_f32_e32 v59, 0, v59
	v_max_f32_e32 v60, 0, v60
	v_max_f32_e32 v61, 0, v61
	v_pk_mul_f32 v[62:63], v[62:63], v[62:63]
	v_pk_mul_f32 v[64:65], v[64:65], v[64:65]
	v_pk_mul_f32 v[58:59], v[58:59], v[58:59]
	v_pk_mul_f32 v[60:61], v[60:61], v[60:61]
	v_cvt_pk_bf16_f32 v62, v62, v63
	v_cvt_pk_bf16_f32 v63, v64, v65
	v_cvt_pk_bf16_f32 v64, v58, v59
	v_cvt_pk_bf16_f32 v65, v60, v61
	v_pk_mul_f32 v[54:55], v[54:55], v[200:201] op_sel_hi:[1,0]
	v_pk_mul_f32 v[56:57], v[56:57], v[200:201] op_sel_hi:[1,0]
	v_pk_mul_f32 v[50:51], v[50:51], v[200:201] op_sel_hi:[1,0]
	v_pk_mul_f32 v[52:53], v[52:53], v[200:201] op_sel_hi:[1,0]
	v_max_f32_e32 v54, 0, v54
	v_max_f32_e32 v55, 0, v55
	v_max_f32_e32 v56, 0, v56
	v_max_f32_e32 v57, 0, v57
	v_max_f32_e32 v50, 0, v50
	v_max_f32_e32 v51, 0, v51
	v_max_f32_e32 v52, 0, v52
	v_max_f32_e32 v53, 0, v53
	v_pk_mul_f32 v[54:55], v[54:55], v[54:55]
	v_pk_mul_f32 v[56:57], v[56:57], v[56:57]
	v_pk_mul_f32 v[50:51], v[50:51], v[50:51]
	v_pk_mul_f32 v[52:53], v[52:53], v[52:53]
	v_cvt_pk_bf16_f32 v54, v54, v55
	v_cvt_pk_bf16_f32 v55, v56, v57
	v_cvt_pk_bf16_f32 v56, v50, v51
	v_cvt_pk_bf16_f32 v57, v52, v53
	v_cndmask_b32_e64 v58, v62, v54, s[92:93]
	v_cndmask_b32_e64 v59, v63, v55, s[92:93]
	v_cndmask_b32_e64 v60, v64, v56, s[92:93]
	v_cndmask_b32_e64 v61, v65, v57, s[92:93]
	v_mov_b32_dpp v50, v58 quad_perm:[1,0,3,2] row_mask:0xf bank_mask:0xf
	v_mov_b32_dpp v51, v59 quad_perm:[1,0,3,2] row_mask:0xf bank_mask:0xf
	v_mov_b32_dpp v52, v60 quad_perm:[1,0,3,2] row_mask:0xf bank_mask:0xf
	v_mov_b32_dpp v53, v61 quad_perm:[1,0,3,2] row_mask:0xf bank_mask:0xf
	v_cndmask_b32_e64 v62, v50, v62, s[92:93]
	v_cndmask_b32_e64 v63, v51, v63, s[92:93]
	v_cndmask_b32_e64 v64, v52, v64, s[92:93]
	v_cndmask_b32_e64 v65, v53, v65, s[92:93]
	v_cndmask_b32_e64 v54, v54, v50, s[92:93]
	v_cndmask_b32_e64 v55, v55, v51, s[92:93]
	v_cndmask_b32_e64 v56, v56, v52, s[92:93]
	v_cndmask_b32_e64 v57, v57, v53, s[92:93]
	global_store_dwordx4 v208, v[62:65], s[64:65] nt
	global_store_dwordx4 v209, v[54:57], s[64:65] nt
	s_waitcnt lgkmcnt(2)
; #define LAS __attribute__((address_space(3)))
; __device__ __forceinline__ unsigned cvt_pk_bf16(float lo, float hi) { unsigned r; asm volatile("v_cvt_pk_bf16_f32 %0, %1, %2" : "=v"(r) : "v"(lo), "v"(hi)); return r; }
;     __device__ __forceinline__ void operator()(const f32x4 (&acc)[2][2][4][2], const Unit& u, int wr, int wc, int fr, int fq) const {
;     ...
;         for (int ai = 0; ai < 2; ++ai)
; #pragma unroll
;             for (int m = 0; m < 4; ++m) {
;                 const float sc = __shfl(rl[ai], 16 * m + fr);
; #pragma unroll
;                 for (int bj = 0; bj < 2; ++bj) {
;                     f32x4 v0 = acc[ai][bj][m][0] * sc, v1 = acc[ai][bj][m][1] * sc;
;                     if (ACT == 1) {
; #pragma unroll
;                         for (int e = 0; e < 4; ++e) { float a = fmaxf(v0[e], 0.f), b = fmaxf(v1[e], 0.f); v0[e] = a * a; v1[e] = b * b; }
;                     }
;                     u32x4 w; w.x = cvt_pk_bf16(v0[0], v0[1]); w.y = cvt_pk_bf16(v0[2], v0[3]); w.z = cvt_pk_bf16(v1[0], v1[1]); w.w = cvt_pk_bf16(v1[2], v1[3]);
;                     *(LAS u32x4*)(sl + fr * 144 + bj * 64 + fq * 16) = w;
;                 }
;                 const int rowb = u.pm * BM + ai * HALF + wr * 64 + m * 16;
; #pragma unroll
;                 for (int i = 0; i < 2; ++i) { const int r = rr + 8 * i; const u32x4 q = *(const LAS u32x4*)(sl + r * 144 + cc * 16);
;                     __builtin_nontemporal_store(q, (u32x4*)(O + (size_t)(rowb + r) * ldc + colw + cc * 8)); }
	s_add_u32 s64, s62, 0x120000
	s_addc_u32 s65, s63, 0
	v_pk_mul_f32 v[46:47], v[46:47], v[202:203] op_sel_hi:[1,0]
	v_pk_mul_f32 v[48:49], v[48:49], v[202:203] op_sel_hi:[1,0]
	v_pk_mul_f32 v[42:43], v[42:43], v[202:203] op_sel_hi:[1,0]
	v_pk_mul_f32 v[44:45], v[44:45], v[202:203] op_sel_hi:[1,0]
	v_max_f32_e32 v46, 0, v46
	v_max_f32_e32 v47, 0, v47
	v_max_f32_e32 v48, 0, v48
	v_max_f32_e32 v49, 0, v49
	v_max_f32_e32 v42, 0, v42
	v_max_f32_e32 v43, 0, v43
	v_max_f32_e32 v44, 0, v44
	v_max_f32_e32 v45, 0, v45
	v_pk_mul_f32 v[46:47], v[46:47], v[46:47]
	v_pk_mul_f32 v[48:49], v[48:49], v[48:49]
	v_pk_mul_f32 v[42:43], v[42:43], v[42:43]
	v_pk_mul_f32 v[44:45], v[44:45], v[44:45]
	v_cvt_pk_bf16_f32 v46, v46, v47
	v_cvt_pk_bf16_f32 v47, v48, v49
	v_cvt_pk_bf16_f32 v48, v42, v43
	v_cvt_pk_bf16_f32 v49, v44, v45
	v_pk_mul_f32 v[38:39], v[38:39], v[202:203] op_sel_hi:[1,0]
	v_pk_mul_f32 v[40:41], v[40:41], v[202:203] op_sel_hi:[1,0]
	v_pk_mul_f32 v[34:35], v[34:35], v[202:203] op_sel_hi:[1,0]
	v_pk_mul_f32 v[36:37], v[36:37], v[202:203] op_sel_hi:[1,0]
	v_max_f32_e32 v38, 0, v38
	v_max_f32_e32 v39, 0, v39
	v_max_f32_e32 v40, 0, v40
	v_max_f32_e32 v41, 0, v41
	v_max_f32_e32 v34, 0, v34
	v_max_f32_e32 v35, 0, v35
	v_max_f32_e32 v36, 0, v36
	v_max_f32_e32 v37, 0, v37
	v_pk_mul_f32 v[38:39], v[38:39], v[38:39]
	v_pk_mul_f32 v[40:41], v[40:41], v[40:41]
	v_pk_mul_f32 v[34:35], v[34:35], v[34:35]
	v_pk_mul_f32 v[36:37], v[36:37], v[36:37]
	v_cvt_pk_bf16_f32 v38, v38, v39
	v_cvt_pk_bf16_f32 v39, v40, v41
	v_cvt_pk_bf16_f32 v40, v34, v35
	v_cvt_pk_bf16_f32 v41, v36, v37
	v_cndmask_b32_e64 v42, v46, v38, s[92:93]
	v_cndmask_b32_e64 v43, v47, v39, s[92:93]
	v_cndmask_b32_e64 v44, v48, v40, s[92:93]
	v_cndmask_b32_e64 v45, v49, v41, s[92:93]
	v_mov_b32_dpp v34, v42 quad_perm:[1,0,3,2] row_mask:0xf bank_mask:0xf
	v_mov_b32_dpp v35, v43 quad_perm:[1,0,3,2] row_mask:0xf bank_mask:0xf
	v_mov_b32_dpp v36, v44 quad_perm:[1,0,3,2] row_mask:0xf bank_mask:0xf
	v_mov_b32_dpp v37, v45 quad_perm:[1,0,3,2] row_mask:0xf bank_mask:0xf
	v_cndmask_b32_e64 v46, v34, v46, s[92:93]
	v_cndmask_b32_e64 v47, v35, v47, s[92:93]
	v_cndmask_b32_e64 v48, v36, v48, s[92:93]
	v_cndmask_b32_e64 v49, v37, v49, s[92:93]
	v_cndmask_b32_e64 v38, v38, v34, s[92:93]
	v_cndmask_b32_e64 v39, v39, v35, s[92:93]
	v_cndmask_b32_e64 v40, v40, v36, s[92:93]
	v_cndmask_b32_e64 v41, v41, v37, s[92:93]
	global_store_dwordx4 v208, v[46:49], s[64:65] nt
	global_store_dwordx4 v209, v[38:41], s[64:65] nt
	s_waitcnt lgkmcnt(1)
; #define LAS __attribute__((address_space(3)))
; __device__ __forceinline__ unsigned cvt_pk_bf16(float lo, float hi) { unsigned r; asm volatile("v_cvt_pk_bf16_f32 %0, %1, %2" : "=v"(r) : "v"(lo), "v"(hi)); return r; }
;     __device__ __forceinline__ void operator()(const f32x4 (&acc)[2][2][4][2], const Unit& u, int wr, int wc, int fr, int fq) const {
;     ...
;         for (int ai = 0; ai < 2; ++ai)
; #pragma unroll
;             for (int m = 0; m < 4; ++m) {
;                 const float sc = __shfl(rl[ai], 16 * m + fr);
; #pragma unroll
;                 for (int bj = 0; bj < 2; ++bj) {
;                     f32x4 v0 = acc[ai][bj][m][0] * sc, v1 = acc[ai][bj][m][1] * sc;
;                     if (ACT == 1) {
; #pragma unroll
;                         for (int e = 0; e < 4; ++e) { float a = fmaxf(v0[e], 0.f), b = fmaxf(v1[e], 0.f); v0[e] = a * a; v1[e] = b * b; }
;                     }
;                     u32x4 w; w.x = cvt_pk_bf16(v0[0], v0[1]); w.y = cvt_pk_bf16(v0[2], v0[3]); w.z = cvt_pk_bf16(v1[0], v1[1]); w.w = cvt_pk_bf16(v1[2], v1[3]);
;                     *(LAS u32x4*)(sl + fr * 144 + bj * 64 + fq * 16) = w;
;                 }
;                 const int rowb = u.pm * BM + ai * HALF + wr * 64 + m * 16;
; #pragma unroll
;                 for (int i = 0; i < 2; ++i) { const int r = rr + 8 * i; const u32x4 q = *(const LAS u32x4*)(sl + r * 144 + cc * 16);
;                     __builtin_nontemporal_store(q, (u32x4*)(O + (size_t)(rowb + r) * ldc + colw + cc * 8)); }
	s_add_u32 s64, s62, 0x140000
	s_addc_u32 s65, s63, 0
	v_pk_mul_f32 v[30:31], v[30:31], v[204:205] op_sel_hi:[1,0]
	v_pk_mul_f32 v[32:33], v[32:33], v[204:205] op_sel_hi:[1,0]
	v_pk_mul_f32 v[26:27], v[26:27], v[204:205] op_sel_hi:[1,0]
	v_pk_mul_f32 v[28:29], v[28:29], v[204:205] op_sel_hi:[1,0]
	v_max_f32_e32 v30, 0, v30
	v_max_f32_e32 v31, 0, v31
	v_max_f32_e32 v32, 0, v32
	v_max_f32_e32 v33, 0, v33
	v_max_f32_e32 v26, 0, v26
	v_max_f32_e32 v27, 0, v27
	v_max_f32_e32 v28, 0, v28
	v_max_f32_e32 v29, 0, v29
	v_pk_mul_f32 v[30:31], v[30:31], v[30:31]
	v_pk_mul_f32 v[32:33], v[32:33], v[32:33]
	v_pk_mul_f32 v[26:27], v[26:27], v[26:27]
	v_pk_mul_f32 v[28:29], v[28:29], v[28:29]
	v_cvt_pk_bf16_f32 v30, v30, v31
	v_cvt_pk_bf16_f32 v31, v32, v33
	v_cvt_pk_bf16_f32 v32, v26, v27
	v_cvt_pk_bf16_f32 v33, v28, v29
	v_pk_mul_f32 v[22:23], v[22:23], v[204:205] op_sel_hi:[1,0]
	v_pk_mul_f32 v[24:25], v[24:25], v[204:205] op_sel_hi:[1,0]
	v_pk_mul_f32 v[18:19], v[18:19], v[204:205] op_sel_hi:[1,0]
	v_pk_mul_f32 v[20:21], v[20:21], v[204:205] op_sel_hi:[1,0]
	v_max_f32_e32 v22, 0, v22
	v_max_f32_e32 v23, 0, v23
	v_max_f32_e32 v24, 0, v24
	v_max_f32_e32 v25, 0, v25
	v_max_f32_e32 v18, 0, v18
	v_max_f32_e32 v19, 0, v19
	v_max_f32_e32 v20, 0, v20
	v_max_f32_e32 v21, 0, v21
	v_pk_mul_f32 v[22:23], v[22:23], v[22:23]
	v_pk_mul_f32 v[24:25], v[24:25], v[24:25]
	v_pk_mul_f32 v[18:19], v[18:19], v[18:19]
	v_pk_mul_f32 v[20:21], v[20:21], v[20:21]
	v_cvt_pk_bf16_f32 v22, v22, v23
	v_cvt_pk_bf16_f32 v23, v24, v25
	v_cvt_pk_bf16_f32 v24, v18, v19
	v_cvt_pk_bf16_f32 v25, v20, v21
	v_cndmask_b32_e64 v26, v30, v22, s[92:93]
	v_cndmask_b32_e64 v27, v31, v23, s[92:93]
	v_cndmask_b32_e64 v28, v32, v24, s[92:93]
	v_cndmask_b32_e64 v29, v33, v25, s[92:93]
	v_mov_b32_dpp v18, v26 quad_perm:[1,0,3,2] row_mask:0xf bank_mask:0xf
	v_mov_b32_dpp v19, v27 quad_perm:[1,0,3,2] row_mask:0xf bank_mask:0xf
	v_mov_b32_dpp v20, v28 quad_perm:[1,0,3,2] row_mask:0xf bank_mask:0xf
	v_mov_b32_dpp v21, v29 quad_perm:[1,0,3,2] row_mask:0xf bank_mask:0xf
	v_cndmask_b32_e64 v30, v18, v30, s[92:93]
	v_cndmask_b32_e64 v31, v19, v31, s[92:93]
	v_cndmask_b32_e64 v32, v20, v32, s[92:93]
	v_cndmask_b32_e64 v33, v21, v33, s[92:93]
	v_cndmask_b32_e64 v22, v22, v18, s[92:93]
	v_cndmask_b32_e64 v23, v23, v19, s[92:93]
	v_cndmask_b32_e64 v24, v24, v20, s[92:93]
	v_cndmask_b32_e64 v25, v25, v21, s[92:93]
	global_store_dwordx4 v208, v[30:33], s[64:65] nt
	global_store_dwordx4 v209, v[22:25], s[64:65] nt
	s_waitcnt lgkmcnt(0)
	s_add_u32 s64, s62, 0x160000
	s_addc_u32 s65, s63, 0
	v_pk_mul_f32 v[14:15], v[14:15], v[206:207] op_sel_hi:[1,0]
	v_pk_mul_f32 v[16:17], v[16:17], v[206:207] op_sel_hi:[1,0]
	v_pk_mul_f32 v[10:11], v[10:11], v[206:207] op_sel_hi:[1,0]
	v_pk_mul_f32 v[12:13], v[12:13], v[206:207] op_sel_hi:[1,0]
	v_max_f32_e32 v14, 0, v14
	v_max_f32_e32 v15, 0, v15
	v_max_f32_e32 v16, 0, v16
	v_max_f32_e32 v17, 0, v17
	v_max_f32_e32 v10, 0, v10
	v_max_f32_e32 v11, 0, v11
	v_max_f32_e32 v12, 0, v12
	v_max_f32_e32 v13, 0, v13
	v_pk_mul_f32 v[14:15], v[14:15], v[14:15]
	v_pk_mul_f32 v[16:17], v[16:17], v[16:17]
	v_pk_mul_f32 v[10:11], v[10:11], v[10:11]
	v_pk_mul_f32 v[12:13], v[12:13], v[12:13]
	v_cvt_pk_bf16_f32 v14, v14, v15
	v_cvt_pk_bf16_f32 v15, v16, v17
	v_cvt_pk_bf16_f32 v16, v10, v11
	v_cvt_pk_bf16_f32 v17, v12, v13
	v_pk_mul_f32 v[6:7], v[6:7], v[206:207] op_sel_hi:[1,0]
	v_pk_mul_f32 v[8:9], v[8:9], v[206:207] op_sel_hi:[1,0]
	v_pk_mul_f32 v[2:3], v[2:3], v[206:207] op_sel_hi:[1,0]
	v_pk_mul_f32 v[4:5], v[4:5], v[206:207] op_sel_hi:[1,0]
	v_max_f32_e32 v6, 0, v6
	v_max_f32_e32 v7, 0, v7
	v_max_f32_e32 v8, 0, v8
	v_max_f32_e32 v9, 0, v9
	v_max_f32_e32 v2, 0, v2
	v_max_f32_e32 v3, 0, v3
	v_max_f32_e32 v4, 0, v4
	v_max_f32_e32 v5, 0, v5
	v_pk_mul_f32 v[6:7], v[6:7], v[6:7]
	v_pk_mul_f32 v[8:9], v[8:9], v[8:9]
	v_pk_mul_f32 v[2:3], v[2:3], v[2:3]
	v_pk_mul_f32 v[4:5], v[4:5], v[4:5]
	v_cvt_pk_bf16_f32 v6, v6, v7
	v_cvt_pk_bf16_f32 v7, v8, v9
	v_cvt_pk_bf16_f32 v8, v2, v3
	v_cvt_pk_bf16_f32 v9, v4, v5
	v_cndmask_b32_e64 v10, v14, v6, s[92:93]
	v_cndmask_b32_e64 v11, v15, v7, s[92:93]
	v_cndmask_b32_e64 v12, v16, v8, s[92:93]
	v_cndmask_b32_e64 v13, v17, v9, s[92:93]
	v_mov_b32_dpp v2, v10 quad_perm:[1,0,3,2] row_mask:0xf bank_mask:0xf
	v_mov_b32_dpp v3, v11 quad_perm:[1,0,3,2] row_mask:0xf bank_mask:0xf
	v_mov_b32_dpp v4, v12 quad_perm:[1,0,3,2] row_mask:0xf bank_mask:0xf
	v_mov_b32_dpp v5, v13 quad_perm:[1,0,3,2] row_mask:0xf bank_mask:0xf
	v_cndmask_b32_e64 v14, v2, v14, s[92:93]
	v_cndmask_b32_e64 v15, v3, v15, s[92:93]
	v_cndmask_b32_e64 v16, v4, v16, s[92:93]
	v_cndmask_b32_e64 v17, v5, v17, s[92:93]
	v_cndmask_b32_e64 v6, v6, v2, s[92:93]
	v_cndmask_b32_e64 v7, v7, v3, s[92:93]
	v_cndmask_b32_e64 v8, v8, v4, s[92:93]
	v_cndmask_b32_e64 v9, v9, v5, s[92:93]
	global_store_dwordx4 v208, v[14:17], s[64:65] nt
	global_store_dwordx4 v209, v[6:9], s[64:65] nt
	s_andn2_b64 vcc, exec, s[38:39]
	s_mov_b64 s[26:27], -1
	s_cbranch_vccnz .LBB0_506
